# GEMM loops: phase-4 LDS-DMA loads reuse phase-2 addresses with offset:128 and M0-128 instead of 64-bit VALU adds
# baseline (speedup 1.0000x reference)
; #define PG8_STAGE(bufoff, gbase, voff) do { _Pragma("unroll") for (int _i = 0; _i < 2; ++_i) \
;         __builtin_amdgcn_global_load_lds((const unsigned*)((const char*)(gbase) + (voff)[_i]), (LAS unsigned*)(lds + (bufoff) + ldsw + _i * 8192), 16, 0, 0); } while (0)
; #define PG8_LDA(dst, b, h) do { _Pragma("unroll") for (int m = 0; m < 4; ++m) _Pragma("unroll") for (int k = 0; k < 2; ++k) dst[m][k] = *(const LAS bf16x8*)(lds + PG8_SA(b, h) + aoff + m * 2048 + k * 1024); } while (0)
; #define PG8_LDB(dst, b, h) do { _Pragma("unroll") for (int n = 0; n < 2; ++n) _Pragma("unroll") for (int k = 0; k < 2; ++k) dst[n][k] = *(const LAS bf16x8*)(lds + PG8_SB(b, h) + boff + n * 2048 + k * 1024); } while (0)
; #define PG8_WAIT_V(n) asm volatile("s_waitcnt vmcnt(" #n ")" ::: "memory")
; #define PG8_WAIT_L(n) asm volatile("s_waitcnt lgkmcnt(" #n ")" ::: "memory")
; #define PG8_BAR __builtin_amdgcn_s_barrier()
; #define PG8_SCHED __builtin_amdgcn_sched_barrier(0)
; template <class Epi, class Sched, bool F8 = false>
; __device__ __forceinline__ void gemm_phase(LAS unsigned char* lds, const Gemm g, const Sched& S, const Epi& E) {
;     ...
;         for (int t = 0; t < nt; t += 2) {
;             const bool last = (t == nt - 2);
;             const char* a1 = cA + (size_t)(t + 1) * kstep;
;             const char* a2 = last ? nA : cA + (size_t)(t + 2) * kstep; const char* b2 = last ? nB : cB + (size_t)(t + 2) * kstep;
;             const char* a3 = a2 + kstep; const char* b3 = b2 + kstep;
;             PG8_LDB(B0, 0, 0); PG8_LDB(B1, 0, 1); PG8_SCHED; PG8_LDA(At, 0, 0); PG8_STAGE(PG8_SA(1, 1), a1 + hstepA, voffA);
;             PG8_WAIT_V(8); PG8_WAIT_L(0); PG8_BAR; PG8_MMA(0, 0, At, B0); PG8_MMA(0, 1, At, B1); PG8_BAR; PG8_SCHED;
;             PG8_LDA(At, 0, 1); PG8_STAGE(PG8_SB(0, 0), b2, voffB); PG8_STAGE(PG8_SB(0, 1), b2 + hstepB, voffB); PG8_STAGE(PG8_SA(0, 0), a2, voffA);
;             PG8_WAIT_V(8); PG8_WAIT_L(0); PG8_BAR; PG8_MMA(1, 0, At, B0); PG8_MMA(1, 1, At, B1); PG8_BAR; PG8_SCHED;
.LBB0_144:
	ds_read_b128 v[72:75], v170
	ds_read_b128 v[76:79], v170 offset:1024
	ds_read_b128 v[80:83], v170 offset:2048
	ds_read_b128 v[88:91], v170 offset:3072
	ds_read_b128 v[162:165], v171
	ds_read_b128 v[174:177], v171 offset:1024
	ds_read_b128 v[178:181], v171 offset:2048
	ds_read_b128 v[182:185], v171 offset:3072
	s_add_u32 s30, s26, 0xfff80080
	s_addc_u32 s31, s27, -1
	s_cmp_eq_u32 s50, 28
	s_cselect_b32 s35, s7, s31
	s_cselect_b32 s34, s19, s30
	s_cselect_b32 s31, s17, s49
	s_cselect_b32 s30, s36, s37
	s_add_i32 m0, s29, 0xc000
	ds_read_b128 v[192:195], v172
	ds_read_b128 v[196:199], v172 offset:1024
	ds_read_b128 v[200:203], v172 offset:2048
	ds_read_b128 v[204:207], v172 offset:3072
	ds_read_b128 v[208:211], v172 offset:4096
	ds_read_b128 v[212:215], v172 offset:5120
	ds_read_b128 v[216:219], v172 offset:6144
	ds_read_b128 v[220:223], v172 offset:7168
	global_load_lds_dwordx4 v152, s[26:27]
	s_add_i32 m0, s29, 0xe000
	s_nop 0
	global_load_lds_dwordx4 v154, s[26:27]
	s_waitcnt vmcnt(8)
	s_waitcnt lgkmcnt(0)
	s_barrier
	s_setprio 1
	s_waitcnt lgkmcnt(0)
	v_mfma_f32_16x16x32_bf16 v[140:143], v[72:75], v[192:195], v[140:143]
	v_mfma_f32_16x16x32_bf16 v[136:139], v[80:83], v[192:195], v[136:139]
	v_mfma_f32_16x16x32_bf16 v[124:127], v[72:75], v[200:203], v[124:127]
	v_mfma_f32_16x16x32_bf16 v[120:123], v[80:83], v[200:203], v[120:123]
	v_mfma_f32_16x16x32_bf16 v[108:111], v[72:75], v[208:211], v[108:111]
	v_mfma_f32_16x16x32_bf16 v[104:107], v[80:83], v[208:211], v[104:107]
	v_mfma_f32_16x16x32_bf16 v[92:95], v[72:75], v[216:219], v[92:95]
	v_mfma_f32_16x16x32_bf16 v[84:87], v[80:83], v[216:219], v[84:87]
	v_mfma_f32_16x16x32_bf16 v[140:143], v[76:79], v[196:199], v[140:143]
	v_mfma_f32_16x16x32_bf16 v[136:139], v[88:91], v[196:199], v[136:139]
	v_mfma_f32_16x16x32_bf16 v[124:127], v[76:79], v[204:207], v[124:127]
	v_mfma_f32_16x16x32_bf16 v[120:123], v[88:91], v[204:207], v[120:123]
	v_mfma_f32_16x16x32_bf16 v[108:111], v[76:79], v[212:215], v[108:111]
	v_mfma_f32_16x16x32_bf16 v[104:107], v[88:91], v[212:215], v[104:107]
	v_mfma_f32_16x16x32_bf16 v[92:95], v[76:79], v[220:223], v[92:95]
	v_mfma_f32_16x16x32_bf16 v[84:87], v[88:91], v[220:223], v[84:87]
	s_setprio 0
	s_setprio 1
	v_mfma_f32_16x16x32_bf16 v[132:135], v[162:165], v[192:195], v[132:135]
	v_mfma_f32_16x16x32_bf16 v[128:131], v[178:181], v[192:195], v[128:131]
	v_mfma_f32_16x16x32_bf16 v[116:119], v[162:165], v[200:203], v[116:119]
	v_mfma_f32_16x16x32_bf16 v[112:115], v[178:181], v[200:203], v[112:115]
	v_mfma_f32_16x16x32_bf16 v[100:103], v[162:165], v[208:211], v[100:103]
	v_mfma_f32_16x16x32_bf16 v[96:99], v[178:181], v[208:211], v[96:99]
	v_mfma_f32_16x16x32_bf16 v[68:71], v[162:165], v[216:219], v[68:71]
	v_mfma_f32_16x16x32_bf16 v[64:67], v[178:181], v[216:219], v[64:67]
	v_mfma_f32_16x16x32_bf16 v[132:135], v[174:177], v[196:199], v[132:135]
	v_mfma_f32_16x16x32_bf16 v[128:131], v[182:185], v[196:199], v[128:131]
	v_mfma_f32_16x16x32_bf16 v[116:119], v[174:177], v[204:207], v[116:119]
	v_mfma_f32_16x16x32_bf16 v[112:115], v[182:185], v[204:207], v[112:115]
	v_mfma_f32_16x16x32_bf16 v[100:103], v[174:177], v[212:215], v[100:103]
	v_mfma_f32_16x16x32_bf16 v[96:99], v[182:185], v[212:215], v[96:99]
	v_mfma_f32_16x16x32_bf16 v[68:71], v[174:177], v[220:223], v[68:71]
	v_mfma_f32_16x16x32_bf16 v[64:67], v[182:185], v[220:223], v[64:67]
	s_setprio 0
	s_barrier
	s_add_i32 s51, s47, s38
	v_lshl_add_u64 v[166:167], s[30:31], 0, v[146:147]
	s_mov_b32 m0, s51
	ds_read_b128 v[192:195], v172 offset:16384
	ds_read_b128 v[196:199], v172 offset:17408
	ds_read_b128 v[200:203], v172 offset:18432
	ds_read_b128 v[204:207], v172 offset:19456
	ds_read_b128 v[208:211], v172 offset:20480
	ds_read_b128 v[212:215], v172 offset:21504
	ds_read_b128 v[216:219], v172 offset:22528
	ds_read_b128 v[220:223], v172 offset:23552
	global_load_lds_dwordx4 v[166:167], off
	s_add_i32 m0, s51, 0x2000
	s_add_u32 s56, s30, 0x80000
	v_lshl_add_u64 v[188:189], s[30:31], 0, v[150:151]
	s_addc_u32 s57, s31, 0
	s_add_i32 s51, s48, s38
	global_load_lds_dwordx4 v[188:189], off
	s_mov_b32 m0, s51
	v_lshl_add_u64 v[226:227], s[34:35], 0, v[148:149]
	global_load_lds_dwordx4 v146, s[56:57]
	s_add_i32 m0, s51, 0x2000
	s_nop 0
	global_load_lds_dwordx4 v150, s[56:57]
	v_lshl_add_u64 v[224:225], s[34:35], 0, v[144:145]
	s_mov_b32 m0, s29
	s_nop 0
	global_load_lds_dwordx4 v[224:225], off
	s_mov_b32 m0, s39
	s_nop 0
	global_load_lds_dwordx4 v[226:227], off
	s_waitcnt vmcnt(8)
	s_waitcnt lgkmcnt(0)
	s_barrier
	s_setprio 1
	s_waitcnt lgkmcnt(0)
	v_mfma_f32_16x16x32_bf16 v[60:63], v[72:75], v[192:195], v[60:63]
	v_mfma_f32_16x16x32_bf16 v[56:59], v[80:83], v[192:195], v[56:59]
	v_mfma_f32_16x16x32_bf16 v[44:47], v[72:75], v[200:203], v[44:47]
	v_mfma_f32_16x16x32_bf16 v[40:43], v[80:83], v[200:203], v[40:43]
	v_mfma_f32_16x16x32_bf16 v[28:31], v[72:75], v[208:211], v[28:31]
	v_mfma_f32_16x16x32_bf16 v[24:27], v[80:83], v[208:211], v[24:27]
	v_mfma_f32_16x16x32_bf16 v[12:15], v[72:75], v[216:219], v[12:15]
	v_mfma_f32_16x16x32_bf16 v[8:11], v[80:83], v[216:219], v[8:11]
	v_mfma_f32_16x16x32_bf16 v[60:63], v[76:79], v[196:199], v[60:63]
	v_mfma_f32_16x16x32_bf16 v[56:59], v[88:91], v[196:199], v[56:59]
	v_mfma_f32_16x16x32_bf16 v[44:47], v[76:79], v[204:207], v[44:47]
	v_mfma_f32_16x16x32_bf16 v[40:43], v[88:91], v[204:207], v[40:43]
	v_mfma_f32_16x16x32_bf16 v[28:31], v[76:79], v[212:215], v[28:31]
	v_mfma_f32_16x16x32_bf16 v[24:27], v[88:91], v[212:215], v[24:27]
	v_mfma_f32_16x16x32_bf16 v[12:15], v[76:79], v[220:223], v[12:15]
	v_mfma_f32_16x16x32_bf16 v[8:11], v[88:91], v[220:223], v[8:11]
	s_setprio 0
	s_setprio 1
	v_mfma_f32_16x16x32_bf16 v[52:55], v[162:165], v[192:195], v[52:55]
	v_mfma_f32_16x16x32_bf16 v[48:51], v[178:181], v[192:195], v[48:51]
	v_mfma_f32_16x16x32_bf16 v[36:39], v[162:165], v[200:203], v[36:39]
	v_mfma_f32_16x16x32_bf16 v[32:35], v[178:181], v[200:203], v[32:35]
	v_mfma_f32_16x16x32_bf16 v[20:23], v[162:165], v[208:211], v[20:23]
	v_mfma_f32_16x16x32_bf16 v[16:19], v[178:181], v[208:211], v[16:19]
	v_mfma_f32_16x16x32_bf16 v[4:7], v[162:165], v[216:219], v[4:7]
	v_mfma_f32_16x16x32_bf16 v[0:3], v[178:181], v[216:219], v[0:3]
	v_mfma_f32_16x16x32_bf16 v[52:55], v[174:177], v[196:199], v[52:55]
	v_mfma_f32_16x16x32_bf16 v[48:51], v[182:185], v[196:199], v[48:51]
	v_mfma_f32_16x16x32_bf16 v[36:39], v[174:177], v[204:207], v[36:39]
	v_mfma_f32_16x16x32_bf16 v[32:35], v[182:185], v[204:207], v[32:35]
	v_mfma_f32_16x16x32_bf16 v[20:23], v[174:177], v[212:215], v[20:23]
	v_mfma_f32_16x16x32_bf16 v[16:19], v[182:185], v[212:215], v[16:19]
	v_mfma_f32_16x16x32_bf16 v[4:7], v[174:177], v[220:223], v[4:7]
	v_mfma_f32_16x16x32_bf16 v[0:3], v[182:185], v[220:223], v[0:3]
	s_setprio 0
	s_barrier
; #define PG8_STAGE(bufoff, gbase, voff) do { _Pragma("unroll") for (int _i = 0; _i < 2; ++_i) \
;         __builtin_amdgcn_global_load_lds((const unsigned*)((const char*)(gbase) + (voff)[_i]), (LAS unsigned*)(lds + (bufoff) + ldsw + _i * 8192), 16, 0, 0); } while (0)
; #define PG8_LDA(dst, b, h) do { _Pragma("unroll") for (int m = 0; m < 4; ++m) _Pragma("unroll") for (int k = 0; k < 2; ++k) dst[m][k] = *(const LAS bf16x8*)(lds + PG8_SA(b, h) + aoff + m * 2048 + k * 1024); } while (0)
; #define PG8_LDB(dst, b, h) do { _Pragma("unroll") for (int n = 0; n < 2; ++n) _Pragma("unroll") for (int k = 0; k < 2; ++k) dst[n][k] = *(const LAS bf16x8*)(lds + PG8_SB(b, h) + boff + n * 2048 + k * 1024); } while (0)
; #define PG8_WAIT_V(n) asm volatile("s_waitcnt vmcnt(" #n ")" ::: "memory")
; #define PG8_WAIT_L(n) asm volatile("s_waitcnt lgkmcnt(" #n ")" ::: "memory")
; #define PG8_BAR __builtin_amdgcn_s_barrier()
; #define PG8_SCHED __builtin_amdgcn_sched_barrier(0)
; template <class Epi, class Sched, bool F8 = false>
; __device__ __forceinline__ void gemm_phase(LAS unsigned char* lds, const Gemm g, const Sched& S, const Epi& E) {
;     ...
;             PG8_LDB(B0, 1, 0); PG8_LDB(B1, 1, 1); PG8_SCHED; PG8_LDA(At, 1, 0); PG8_STAGE(PG8_SA(0, 1), a2 + hstepA, voffA);
;             PG8_WAIT_V(8); PG8_WAIT_L(0); PG8_BAR; PG8_MMA(0, 0, At, B0); PG8_MMA(0, 1, At, B1); PG8_BAR; PG8_SCHED;
;             PG8_LDA(At, 1, 1); PG8_STAGE(PG8_SB(1, 0), b3, voffB); PG8_STAGE(PG8_SB(1, 1), b3 + hstepB, voffB); PG8_STAGE(PG8_SA(1, 0), a3, voffA);
;             PG8_WAIT_V(8); PG8_WAIT_L(0); PG8_BAR; PG8_MMA(1, 0, At, B0); PG8_MMA(1, 1, At, B1); PG8_BAR; PG8_SCHED;
;         }
;         if (wr == 0) PG8_BAR;
	s_add_i32 s51, 0, 0x18000
	s_add_i32 s53, 0, 0x1c000
	v_add_u32_e32 v88, s51, v168
	v_add_u32_e32 v173, s53, v168
	ds_read_b128 v[72:75], v88
	ds_read_b128 v[76:79], v88 offset:1024
	ds_read_b128 v[80:83], v88 offset:2048
	ds_read_b128 v[88:91], v88 offset:3072
	ds_read_b128 v[162:165], v173
	ds_read_b128 v[174:177], v173 offset:1024
	ds_read_b128 v[178:181], v173 offset:2048
	ds_read_b128 v[182:185], v173 offset:3072
	s_add_u32 s34, s34, 0x80000
	s_addc_u32 s35, s35, 0
	s_mov_b32 m0, s40
	ds_read_b128 v[192:195], v172 offset:32768
	ds_read_b128 v[196:199], v172 offset:33792
	ds_read_b128 v[200:203], v172 offset:34816
	ds_read_b128 v[204:207], v172 offset:35840
	ds_read_b128 v[208:211], v172 offset:36864
	ds_read_b128 v[212:215], v172 offset:37888
	ds_read_b128 v[216:219], v172 offset:38912
	ds_read_b128 v[220:223], v172 offset:39936
	global_load_lds_dwordx4 v144, s[34:35]
	s_mov_b32 m0, s41
	s_nop 0
	global_load_lds_dwordx4 v148, s[34:35]
	s_waitcnt vmcnt(8)
	s_waitcnt lgkmcnt(0)
	s_barrier
	s_setprio 1
	s_waitcnt lgkmcnt(0)
	v_mfma_f32_16x16x32_bf16 v[140:143], v[72:75], v[192:195], v[140:143]
	v_mfma_f32_16x16x32_bf16 v[136:139], v[80:83], v[192:195], v[136:139]
	v_mfma_f32_16x16x32_bf16 v[124:127], v[72:75], v[200:203], v[124:127]
	v_mfma_f32_16x16x32_bf16 v[120:123], v[80:83], v[200:203], v[120:123]
	v_mfma_f32_16x16x32_bf16 v[108:111], v[72:75], v[208:211], v[108:111]
	v_mfma_f32_16x16x32_bf16 v[104:107], v[80:83], v[208:211], v[104:107]
	v_mfma_f32_16x16x32_bf16 v[92:95], v[72:75], v[216:219], v[92:95]
	v_mfma_f32_16x16x32_bf16 v[84:87], v[80:83], v[216:219], v[84:87]
	v_mfma_f32_16x16x32_bf16 v[140:143], v[76:79], v[196:199], v[140:143]
	v_mfma_f32_16x16x32_bf16 v[136:139], v[88:91], v[196:199], v[136:139]
	v_mfma_f32_16x16x32_bf16 v[124:127], v[76:79], v[204:207], v[124:127]
	v_mfma_f32_16x16x32_bf16 v[120:123], v[88:91], v[204:207], v[120:123]
	v_mfma_f32_16x16x32_bf16 v[108:111], v[76:79], v[212:215], v[108:111]
	v_mfma_f32_16x16x32_bf16 v[104:107], v[88:91], v[212:215], v[104:107]
	v_mfma_f32_16x16x32_bf16 v[92:95], v[76:79], v[220:223], v[92:95]
	v_mfma_f32_16x16x32_bf16 v[84:87], v[88:91], v[220:223], v[84:87]
	s_setprio 0
	s_setprio 1
	v_mfma_f32_16x16x32_bf16 v[132:135], v[162:165], v[192:195], v[132:135]
	v_mfma_f32_16x16x32_bf16 v[128:131], v[178:181], v[192:195], v[128:131]
	v_mfma_f32_16x16x32_bf16 v[116:119], v[162:165], v[200:203], v[116:119]
	v_mfma_f32_16x16x32_bf16 v[112:115], v[178:181], v[200:203], v[112:115]
	v_mfma_f32_16x16x32_bf16 v[100:103], v[162:165], v[208:211], v[100:103]
	v_mfma_f32_16x16x32_bf16 v[96:99], v[178:181], v[208:211], v[96:99]
	v_mfma_f32_16x16x32_bf16 v[68:71], v[162:165], v[216:219], v[68:71]
	v_mfma_f32_16x16x32_bf16 v[64:67], v[178:181], v[216:219], v[64:67]
	v_mfma_f32_16x16x32_bf16 v[132:135], v[174:177], v[196:199], v[132:135]
	v_mfma_f32_16x16x32_bf16 v[128:131], v[182:185], v[196:199], v[128:131]
	v_mfma_f32_16x16x32_bf16 v[116:119], v[174:177], v[204:207], v[116:119]
	v_mfma_f32_16x16x32_bf16 v[112:115], v[182:185], v[204:207], v[112:115]
	v_mfma_f32_16x16x32_bf16 v[100:103], v[174:177], v[212:215], v[100:103]
	v_mfma_f32_16x16x32_bf16 v[96:99], v[182:185], v[212:215], v[96:99]
	v_mfma_f32_16x16x32_bf16 v[68:71], v[174:177], v[220:223], v[68:71]
	v_mfma_f32_16x16x32_bf16 v[64:67], v[182:185], v[220:223], v[64:67]
	s_setprio 0
	s_barrier
	s_add_i32 s34, s51, s38
	s_add_i32 m0, s34, 0xffffff80
	ds_read_b128 v[192:195], v172 offset:49152
	ds_read_b128 v[196:199], v172 offset:50176
	ds_read_b128 v[200:203], v172 offset:51200
	ds_read_b128 v[204:207], v172 offset:52224
	ds_read_b128 v[208:211], v172 offset:53248
	ds_read_b128 v[212:215], v172 offset:54272
	ds_read_b128 v[216:219], v172 offset:55296
	ds_read_b128 v[220:223], v172 offset:56320
	global_load_lds_dwordx4 v[166:167], off offset:128
	s_add_i32 m0, s34, 0x1f80
	s_add_u32 s30, s30, 0x80080
	s_addc_u32 s31, s31, 0
	s_add_i32 s34, s53, s38
	global_load_lds_dwordx4 v[188:189], off offset:128
	s_mov_b32 m0, s34
	s_nop 0
	global_load_lds_dwordx4 v146, s[30:31]
	s_add_i32 m0, s34, 0x2000
	s_nop 0
	global_load_lds_dwordx4 v150, s[30:31]
	s_add_i32 m0, s43, 0xffffff80
	s_nop 0
	global_load_lds_dwordx4 v[224:225], off offset:128
	s_add_i32 m0, s44, 0xffffff80
	s_nop 0
	global_load_lds_dwordx4 v[226:227], off offset:128
	s_waitcnt vmcnt(8)
	s_waitcnt lgkmcnt(0)
	s_barrier
	s_setprio 1
	s_waitcnt lgkmcnt(0)
	v_mfma_f32_16x16x32_bf16 v[60:63], v[72:75], v[192:195], v[60:63]
	v_mfma_f32_16x16x32_bf16 v[56:59], v[80:83], v[192:195], v[56:59]
	v_mfma_f32_16x16x32_bf16 v[44:47], v[72:75], v[200:203], v[44:47]
	v_mfma_f32_16x16x32_bf16 v[40:43], v[80:83], v[200:203], v[40:43]
	v_mfma_f32_16x16x32_bf16 v[28:31], v[72:75], v[208:211], v[28:31]
	v_mfma_f32_16x16x32_bf16 v[24:27], v[80:83], v[208:211], v[24:27]
	v_mfma_f32_16x16x32_bf16 v[12:15], v[72:75], v[216:219], v[12:15]
	v_mfma_f32_16x16x32_bf16 v[8:11], v[80:83], v[216:219], v[8:11]
	v_mfma_f32_16x16x32_bf16 v[60:63], v[76:79], v[196:199], v[60:63]
	v_mfma_f32_16x16x32_bf16 v[56:59], v[88:91], v[196:199], v[56:59]
	v_mfma_f32_16x16x32_bf16 v[44:47], v[76:79], v[204:207], v[44:47]
	v_mfma_f32_16x16x32_bf16 v[40:43], v[88:91], v[204:207], v[40:43]
	v_mfma_f32_16x16x32_bf16 v[28:31], v[76:79], v[212:215], v[28:31]
	v_mfma_f32_16x16x32_bf16 v[24:27], v[88:91], v[212:215], v[24:27]
	v_mfma_f32_16x16x32_bf16 v[12:15], v[76:79], v[220:223], v[12:15]
	v_mfma_f32_16x16x32_bf16 v[8:11], v[88:91], v[220:223], v[8:11]
	s_setprio 0
	s_setprio 1
	v_mfma_f32_16x16x32_bf16 v[52:55], v[162:165], v[192:195], v[52:55]
	v_mfma_f32_16x16x32_bf16 v[48:51], v[178:181], v[192:195], v[48:51]
	v_mfma_f32_16x16x32_bf16 v[36:39], v[162:165], v[200:203], v[36:39]
	v_mfma_f32_16x16x32_bf16 v[32:35], v[178:181], v[200:203], v[32:35]
	v_mfma_f32_16x16x32_bf16 v[20:23], v[162:165], v[208:211], v[20:23]
	v_mfma_f32_16x16x32_bf16 v[16:19], v[178:181], v[208:211], v[16:19]
	v_mfma_f32_16x16x32_bf16 v[4:7], v[162:165], v[216:219], v[4:7]
	v_mfma_f32_16x16x32_bf16 v[0:3], v[178:181], v[216:219], v[0:3]
	v_mfma_f32_16x16x32_bf16 v[52:55], v[174:177], v[196:199], v[52:55]
	v_mfma_f32_16x16x32_bf16 v[48:51], v[182:185], v[196:199], v[48:51]
	v_mfma_f32_16x16x32_bf16 v[36:39], v[174:177], v[204:207], v[36:39]
	v_mfma_f32_16x16x32_bf16 v[32:35], v[182:185], v[204:207], v[32:35]
	v_mfma_f32_16x16x32_bf16 v[20:23], v[174:177], v[212:215], v[20:23]
	v_mfma_f32_16x16x32_bf16 v[16:19], v[182:185], v[212:215], v[16:19]
	v_mfma_f32_16x16x32_bf16 v[4:7], v[174:177], v[220:223], v[4:7]
	v_mfma_f32_16x16x32_bf16 v[0:3], v[182:185], v[220:223], v[0:3]
	s_setprio 0
	s_barrier
	s_add_i32 s50, s50, 2
	s_add_u32 s26, s26, 0x100
	s_addc_u32 s27, s27, 0
	s_add_u32 s37, s37, 0x100
	s_addc_u32 s49, s49, 0
	s_cmp_gt_u32 s50, 29
	s_cbranch_scc0 .LBB0_144
	s_and_b64 vcc, exec, s[14:15]
	s_cbranch_vccz .LBB0_147
	s_barrier

; #define PG8_STAGE(bufoff, gbase, voff) do { _Pragma("unroll") for (int _i = 0; _i < 2; ++_i) \
;         __builtin_amdgcn_global_load_lds((const unsigned*)((const char*)(gbase) + (voff)[_i]), (LAS unsigned*)(lds + (bufoff) + ldsw + _i * 8192), 16, 0, 0); } while (0)
; #define PG8_LDA(dst, b, h) do { _Pragma("unroll") for (int m = 0; m < 4; ++m) _Pragma("unroll") for (int k = 0; k < 2; ++k) dst[m][k] = *(const LAS bf16x8*)(lds + PG8_SA(b, h) + aoff + m * 2048 + k * 1024); } while (0)
; #define PG8_LDB(dst, b, h) do { _Pragma("unroll") for (int n = 0; n < 2; ++n) _Pragma("unroll") for (int k = 0; k < 2; ++k) dst[n][k] = *(const LAS bf16x8*)(lds + PG8_SB(b, h) + boff + n * 2048 + k * 1024); } while (0)
; #define PG8_WAIT_V(n) asm volatile("s_waitcnt vmcnt(" #n ")" ::: "memory")
; #define PG8_WAIT_L(n) asm volatile("s_waitcnt lgkmcnt(" #n ")" ::: "memory")
; #define PG8_BAR __builtin_amdgcn_s_barrier()
; #define PG8_SCHED __builtin_amdgcn_sched_barrier(0)
; template <class Epi, class Sched, bool F8 = false>
; __device__ __forceinline__ void gemm_phase(LAS unsigned char* lds, const Gemm g, const Sched& S, const Epi& E) {
;     ...
;         for (int t = 0; t < nt; t += 2) {
;             const bool last = (t == nt - 2);
;             const char* a1 = cA + (size_t)(t + 1) * kstep;
;             const char* a2 = last ? nA : cA + (size_t)(t + 2) * kstep; const char* b2 = last ? nB : cB + (size_t)(t + 2) * kstep;
;             const char* a3 = a2 + kstep; const char* b3 = b2 + kstep;
;             PG8_LDB(B0, 0, 0); PG8_LDB(B1, 0, 1); PG8_SCHED; PG8_LDA(At, 0, 0); PG8_STAGE(PG8_SA(1, 1), a1 + hstepA, voffA);
;             PG8_WAIT_V(8); PG8_WAIT_L(0); PG8_BAR; PG8_MMA(0, 0, At, B0); PG8_MMA(0, 1, At, B1); PG8_BAR; PG8_SCHED;
;             PG8_LDA(At, 0, 1); PG8_STAGE(PG8_SB(0, 0), b2, voffB); PG8_STAGE(PG8_SB(0, 1), b2 + hstepB, voffB); PG8_STAGE(PG8_SA(0, 0), a2, voffA);
;             PG8_WAIT_V(8); PG8_WAIT_L(0); PG8_BAR; PG8_MMA(1, 0, At, B0); PG8_MMA(1, 1, At, B1); PG8_BAR; PG8_SCHED;
.LBB0_208:
	ds_read_b128 v[152:155], v189
	ds_read_b128 v[156:159], v189 offset:1024
	ds_read_b128 v[144:147], v189 offset:2048
	ds_read_b128 v[148:151], v189 offset:3072
	ds_read_b128 v[136:139], v191
	ds_read_b128 v[140:143], v191 offset:1024
	ds_read_b128 v[128:131], v191 offset:2048
	ds_read_b128 v[132:135], v191 offset:3072
	s_add_u32 s30, s28, 0xfffc0080
	s_addc_u32 s31, s29, -1
	s_cmp_eq_u32 s53, 12
	s_cselect_b32 s35, s21, s31
	s_cselect_b32 s34, s48, s30
	s_cselect_b32 s31, s19, s51
	s_cselect_b32 s30, s49, s50
	s_add_i32 m0, s27, 0xc000
	ds_read_b128 v[178:181], v192
	ds_read_b128 v[182:185], v192 offset:1024
	ds_read_b128 v[194:197], v192 offset:2048
	ds_read_b128 v[198:201], v192 offset:3072
	ds_read_b128 v[202:205], v192 offset:4096
	ds_read_b128 v[206:209], v192 offset:5120
	ds_read_b128 v[210:213], v192 offset:6144
	ds_read_b128 v[214:217], v192 offset:7168
	global_load_lds_dwordx4 v170, s[28:29]
	s_add_i32 m0, s27, 0xe000
	s_nop 0
	global_load_lds_dwordx4 v172, s[28:29]
	s_waitcnt vmcnt(8)
	s_waitcnt lgkmcnt(0)
	s_barrier
	s_setprio 1
	s_waitcnt lgkmcnt(0)
	v_mfma_scale_f32_16x16x128_f8f6f4 v[124:127], v[152:159], v[178:185], v[124:127], v254, v254 op_sel_hi:[0,0,0]
	v_mfma_scale_f32_16x16x128_f8f6f4 v[120:123], v[144:151], v[178:185], v[120:123], v254, v254 op_sel_hi:[0,0,0]
	v_mfma_scale_f32_16x16x128_f8f6f4 v[108:111], v[152:159], v[194:201], v[108:111], v254, v254 op_sel_hi:[0,0,0]
	v_mfma_scale_f32_16x16x128_f8f6f4 v[104:107], v[144:151], v[194:201], v[104:107], v254, v254 op_sel_hi:[0,0,0]
	v_mfma_scale_f32_16x16x128_f8f6f4 v[92:95], v[152:159], v[202:209], v[92:95], v254, v254 op_sel_hi:[0,0,0]
	v_mfma_scale_f32_16x16x128_f8f6f4 v[88:91], v[144:151], v[202:209], v[88:91], v254, v254 op_sel_hi:[0,0,0]
	v_mfma_scale_f32_16x16x128_f8f6f4 v[76:79], v[152:159], v[210:217], v[76:79], v254, v254 op_sel_hi:[0,0,0]
	v_mfma_scale_f32_16x16x128_f8f6f4 v[72:75], v[144:151], v[210:217], v[72:75], v254, v254 op_sel_hi:[0,0,0]
	s_setprio 0
	s_setprio 1
	v_mfma_scale_f32_16x16x128_f8f6f4 v[116:119], v[136:143], v[178:185], v[116:119], v254, v254 op_sel_hi:[0,0,0]
	v_mfma_scale_f32_16x16x128_f8f6f4 v[112:115], v[128:135], v[178:185], v[112:115], v254, v254 op_sel_hi:[0,0,0]
	v_mfma_scale_f32_16x16x128_f8f6f4 v[100:103], v[136:143], v[194:201], v[100:103], v254, v254 op_sel_hi:[0,0,0]
	v_mfma_scale_f32_16x16x128_f8f6f4 v[96:99], v[128:135], v[194:201], v[96:99], v254, v254 op_sel_hi:[0,0,0]
	v_mfma_scale_f32_16x16x128_f8f6f4 v[84:87], v[136:143], v[202:209], v[84:87], v254, v254 op_sel_hi:[0,0,0]
	v_mfma_scale_f32_16x16x128_f8f6f4 v[80:83], v[128:135], v[202:209], v[80:83], v254, v254 op_sel_hi:[0,0,0]
	v_mfma_scale_f32_16x16x128_f8f6f4 v[68:71], v[136:143], v[210:217], v[68:71], v254, v254 op_sel_hi:[0,0,0]
	v_mfma_scale_f32_16x16x128_f8f6f4 v[64:67], v[128:135], v[210:217], v[64:67], v254, v254 op_sel_hi:[0,0,0]
	s_setprio 0
	s_barrier
	s_add_i32 s56, s43, s17
	v_lshl_add_u64 v[178:179], s[30:31], 0, v[166:167]
	s_mov_b32 m0, s56
	ds_read_b128 v[194:197], v192 offset:16384
	ds_read_b128 v[198:201], v192 offset:17408
	ds_read_b128 v[202:205], v192 offset:18432
	ds_read_b128 v[206:209], v192 offset:19456
	ds_read_b128 v[210:213], v192 offset:20480
	ds_read_b128 v[214:217], v192 offset:21504
	ds_read_b128 v[218:221], v192 offset:22528
	ds_read_b128 v[222:225], v192 offset:23552
	global_load_lds_dwordx4 v[178:179], off
	s_add_i32 m0, s56, 0x2000
	s_add_u32 s56, s30, 0x40000
	v_lshl_add_u64 v[180:181], s[30:31], 0, v[162:163]
	s_addc_u32 s57, s31, 0
	s_add_i32 s58, s44, s17
	global_load_lds_dwordx4 v[180:181], off
	s_mov_b32 m0, s58
	v_lshl_add_u64 v[184:185], s[34:35], 0, v[164:165]
	global_load_lds_dwordx4 v166, s[56:57]
	s_add_i32 m0, s58, 0x2000
	s_nop 0
	global_load_lds_dwordx4 v162, s[56:57]
	v_lshl_add_u64 v[182:183], s[34:35], 0, v[168:169]
	s_mov_b32 m0, s27
	s_nop 0
	global_load_lds_dwordx4 v[182:183], off
	s_mov_b32 m0, s37
	s_nop 0
	global_load_lds_dwordx4 v[184:185], off
	s_waitcnt vmcnt(8)
	s_waitcnt lgkmcnt(0)
	s_barrier
	s_setprio 1
	s_waitcnt lgkmcnt(0)
	v_mfma_scale_f32_16x16x128_f8f6f4 v[60:63], v[152:159], v[194:201], v[60:63], v254, v254 op_sel_hi:[0,0,0]
	v_mfma_scale_f32_16x16x128_f8f6f4 v[56:59], v[144:151], v[194:201], v[56:59], v254, v254 op_sel_hi:[0,0,0]
	v_mfma_scale_f32_16x16x128_f8f6f4 v[44:47], v[152:159], v[202:209], v[44:47], v254, v254 op_sel_hi:[0,0,0]
	v_mfma_scale_f32_16x16x128_f8f6f4 v[40:43], v[144:151], v[202:209], v[40:43], v254, v254 op_sel_hi:[0,0,0]
	v_mfma_scale_f32_16x16x128_f8f6f4 v[28:31], v[152:159], v[210:217], v[28:31], v254, v254 op_sel_hi:[0,0,0]
	v_mfma_scale_f32_16x16x128_f8f6f4 v[24:27], v[144:151], v[210:217], v[24:27], v254, v254 op_sel_hi:[0,0,0]
	v_mfma_scale_f32_16x16x128_f8f6f4 v[12:15], v[152:159], v[218:225], v[12:15], v254, v254 op_sel_hi:[0,0,0]
	v_mfma_scale_f32_16x16x128_f8f6f4 v[8:11], v[144:151], v[218:225], v[8:11], v254, v254 op_sel_hi:[0,0,0]
	s_setprio 0
	s_setprio 1
	v_mfma_scale_f32_16x16x128_f8f6f4 v[52:55], v[136:143], v[194:201], v[52:55], v254, v254 op_sel_hi:[0,0,0]
	v_mfma_scale_f32_16x16x128_f8f6f4 v[48:51], v[128:135], v[194:201], v[48:51], v254, v254 op_sel_hi:[0,0,0]
	v_mfma_scale_f32_16x16x128_f8f6f4 v[36:39], v[136:143], v[202:209], v[36:39], v254, v254 op_sel_hi:[0,0,0]
	v_mfma_scale_f32_16x16x128_f8f6f4 v[32:35], v[128:135], v[202:209], v[32:35], v254, v254 op_sel_hi:[0,0,0]
	v_mfma_scale_f32_16x16x128_f8f6f4 v[20:23], v[136:143], v[210:217], v[20:23], v254, v254 op_sel_hi:[0,0,0]
	v_mfma_scale_f32_16x16x128_f8f6f4 v[16:19], v[128:135], v[210:217], v[16:19], v254, v254 op_sel_hi:[0,0,0]
	v_mfma_scale_f32_16x16x128_f8f6f4 v[4:7], v[136:143], v[218:225], v[4:7], v254, v254 op_sel_hi:[0,0,0]
	v_mfma_scale_f32_16x16x128_f8f6f4 v[0:3], v[128:135], v[218:225], v[0:3], v254, v254 op_sel_hi:[0,0,0]
	s_setprio 0
	s_barrier
; #define PG8_STAGE(bufoff, gbase, voff) do { _Pragma("unroll") for (int _i = 0; _i < 2; ++_i) \
;         __builtin_amdgcn_global_load_lds((const unsigned*)((const char*)(gbase) + (voff)[_i]), (LAS unsigned*)(lds + (bufoff) + ldsw + _i * 8192), 16, 0, 0); } while (0)
; #define PG8_LDA(dst, b, h) do { _Pragma("unroll") for (int m = 0; m < 4; ++m) _Pragma("unroll") for (int k = 0; k < 2; ++k) dst[m][k] = *(const LAS bf16x8*)(lds + PG8_SA(b, h) + aoff + m * 2048 + k * 1024); } while (0)
; #define PG8_LDB(dst, b, h) do { _Pragma("unroll") for (int n = 0; n < 2; ++n) _Pragma("unroll") for (int k = 0; k < 2; ++k) dst[n][k] = *(const LAS bf16x8*)(lds + PG8_SB(b, h) + boff + n * 2048 + k * 1024); } while (0)
; #define PG8_WAIT_V(n) asm volatile("s_waitcnt vmcnt(" #n ")" ::: "memory")
; #define PG8_WAIT_L(n) asm volatile("s_waitcnt lgkmcnt(" #n ")" ::: "memory")
; #define PG8_BAR __builtin_amdgcn_s_barrier()
; #define PG8_SCHED __builtin_amdgcn_sched_barrier(0)
; template <class Epi, class Sched, bool F8 = false>
; __device__ __forceinline__ void gemm_phase(LAS unsigned char* lds, const Gemm g, const Sched& S, const Epi& E) {
;     ...
;             PG8_LDB(B0, 1, 0); PG8_LDB(B1, 1, 1); PG8_SCHED; PG8_LDA(At, 1, 0); PG8_STAGE(PG8_SA(0, 1), a2 + hstepA, voffA);
;             PG8_WAIT_V(8); PG8_WAIT_L(0); PG8_BAR; PG8_MMA(0, 0, At, B0); PG8_MMA(0, 1, At, B1); PG8_BAR; PG8_SCHED;
;             PG8_LDA(At, 1, 1); PG8_STAGE(PG8_SB(1, 0), b3, voffB); PG8_STAGE(PG8_SB(1, 1), b3 + hstepB, voffB); PG8_STAGE(PG8_SA(1, 0), a3, voffA);
;             PG8_WAIT_V(8); PG8_WAIT_L(0); PG8_BAR; PG8_MMA(1, 0, At, B0); PG8_MMA(1, 1, At, B1); PG8_BAR; PG8_SCHED;
;         }
;         if (wr == 0) PG8_BAR;
	s_add_i32 s56, 0, 0x18000
	v_add_u32_e32 v128, s56, v187
	s_add_i32 s57, 0, 0x1c000
	ds_read_b128 v[152:155], v128
	ds_read_b128 v[156:159], v128 offset:1024
	ds_read_b128 v[144:147], v128 offset:2048
	ds_read_b128 v[148:151], v128 offset:3072
	v_add_u32_e32 v128, s57, v187
	ds_read_b128 v[136:139], v128
	ds_read_b128 v[140:143], v128 offset:1024
	ds_read_b128 v[132:135], v128 offset:3072
	ds_read_b128 v[128:131], v128 offset:2048
	s_add_u32 s34, s34, 0x40000
	s_addc_u32 s35, s35, 0
	s_mov_b32 m0, s38
	ds_read_b128 v[194:197], v192 offset:32768
	ds_read_b128 v[198:201], v192 offset:33792
	ds_read_b128 v[202:205], v192 offset:34816
	ds_read_b128 v[206:209], v192 offset:35840
	ds_read_b128 v[210:213], v192 offset:36864
	ds_read_b128 v[214:217], v192 offset:37888
	ds_read_b128 v[218:221], v192 offset:38912
	ds_read_b128 v[222:225], v192 offset:39936
	global_load_lds_dwordx4 v168, s[34:35]
	s_mov_b32 m0, s39
	s_nop 0
	global_load_lds_dwordx4 v164, s[34:35]
	s_waitcnt vmcnt(8)
	s_waitcnt lgkmcnt(0)
	s_barrier
	s_setprio 1
	s_waitcnt lgkmcnt(0)
	v_mfma_scale_f32_16x16x128_f8f6f4 v[124:127], v[152:159], v[194:201], v[124:127], v254, v254 op_sel_hi:[0,0,0]
	v_mfma_scale_f32_16x16x128_f8f6f4 v[120:123], v[144:151], v[194:201], v[120:123], v254, v254 op_sel_hi:[0,0,0]
	v_mfma_scale_f32_16x16x128_f8f6f4 v[108:111], v[152:159], v[202:209], v[108:111], v254, v254 op_sel_hi:[0,0,0]
	v_mfma_scale_f32_16x16x128_f8f6f4 v[104:107], v[144:151], v[202:209], v[104:107], v254, v254 op_sel_hi:[0,0,0]
	v_mfma_scale_f32_16x16x128_f8f6f4 v[92:95], v[152:159], v[210:217], v[92:95], v254, v254 op_sel_hi:[0,0,0]
	v_mfma_scale_f32_16x16x128_f8f6f4 v[88:91], v[144:151], v[210:217], v[88:91], v254, v254 op_sel_hi:[0,0,0]
	v_mfma_scale_f32_16x16x128_f8f6f4 v[76:79], v[152:159], v[218:225], v[76:79], v254, v254 op_sel_hi:[0,0,0]
	v_mfma_scale_f32_16x16x128_f8f6f4 v[72:75], v[144:151], v[218:225], v[72:75], v254, v254 op_sel_hi:[0,0,0]
	s_setprio 0
	s_setprio 1
	v_mfma_scale_f32_16x16x128_f8f6f4 v[116:119], v[136:143], v[194:201], v[116:119], v254, v254 op_sel_hi:[0,0,0]
	v_mfma_scale_f32_16x16x128_f8f6f4 v[112:115], v[128:135], v[194:201], v[112:115], v254, v254 op_sel_hi:[0,0,0]
	v_mfma_scale_f32_16x16x128_f8f6f4 v[100:103], v[136:143], v[202:209], v[100:103], v254, v254 op_sel_hi:[0,0,0]
	v_mfma_scale_f32_16x16x128_f8f6f4 v[96:99], v[128:135], v[202:209], v[96:99], v254, v254 op_sel_hi:[0,0,0]
	v_mfma_scale_f32_16x16x128_f8f6f4 v[84:87], v[136:143], v[210:217], v[84:87], v254, v254 op_sel_hi:[0,0,0]
	v_mfma_scale_f32_16x16x128_f8f6f4 v[80:83], v[128:135], v[210:217], v[80:83], v254, v254 op_sel_hi:[0,0,0]
	v_mfma_scale_f32_16x16x128_f8f6f4 v[68:71], v[136:143], v[218:225], v[68:71], v254, v254 op_sel_hi:[0,0,0]
	v_mfma_scale_f32_16x16x128_f8f6f4 v[64:67], v[128:135], v[218:225], v[64:67], v254, v254 op_sel_hi:[0,0,0]
	s_setprio 0
	s_barrier
	s_add_i32 s34, s56, s17
	s_add_i32 m0, s34, 0xffffff80
	ds_read_b128 v[194:197], v192 offset:49152
	ds_read_b128 v[198:201], v192 offset:50176
	ds_read_b128 v[202:205], v192 offset:51200
	ds_read_b128 v[206:209], v192 offset:52224
	ds_read_b128 v[210:213], v192 offset:53248
	ds_read_b128 v[214:217], v192 offset:54272
	ds_read_b128 v[218:221], v192 offset:55296
	ds_read_b128 v[222:225], v192 offset:56320
	global_load_lds_dwordx4 v[178:179], off offset:128
	s_add_i32 m0, s34, 0x1f80
	s_add_u32 s30, s30, 0x40080
	s_addc_u32 s31, s31, 0
	s_add_i32 s34, s57, s17
	global_load_lds_dwordx4 v[180:181], off offset:128
	s_mov_b32 m0, s34
	s_nop 0
	global_load_lds_dwordx4 v166, s[30:31]
	s_add_i32 m0, s34, 0x2000
	s_nop 0
	global_load_lds_dwordx4 v162, s[30:31]
	s_add_i32 m0, s41, 0xffffff80
	s_nop 0
	global_load_lds_dwordx4 v[182:183], off offset:128
	s_add_i32 m0, s42, 0xffffff80
	s_nop 0
	global_load_lds_dwordx4 v[184:185], off offset:128
	s_waitcnt vmcnt(8)
	s_waitcnt lgkmcnt(0)
	s_barrier
	s_setprio 1
	s_waitcnt lgkmcnt(0)
	v_mfma_scale_f32_16x16x128_f8f6f4 v[60:63], v[152:159], v[194:201], v[60:63], v254, v254 op_sel_hi:[0,0,0]
	v_mfma_scale_f32_16x16x128_f8f6f4 v[56:59], v[144:151], v[194:201], v[56:59], v254, v254 op_sel_hi:[0,0,0]
	v_mfma_scale_f32_16x16x128_f8f6f4 v[44:47], v[152:159], v[202:209], v[44:47], v254, v254 op_sel_hi:[0,0,0]
	v_mfma_scale_f32_16x16x128_f8f6f4 v[40:43], v[144:151], v[202:209], v[40:43], v254, v254 op_sel_hi:[0,0,0]
	v_mfma_scale_f32_16x16x128_f8f6f4 v[28:31], v[152:159], v[210:217], v[28:31], v254, v254 op_sel_hi:[0,0,0]
	v_mfma_scale_f32_16x16x128_f8f6f4 v[24:27], v[144:151], v[210:217], v[24:27], v254, v254 op_sel_hi:[0,0,0]
	v_mfma_scale_f32_16x16x128_f8f6f4 v[12:15], v[152:159], v[218:225], v[12:15], v254, v254 op_sel_hi:[0,0,0]
	v_mfma_scale_f32_16x16x128_f8f6f4 v[8:11], v[144:151], v[218:225], v[8:11], v254, v254 op_sel_hi:[0,0,0]
	s_setprio 0
	s_setprio 1
	v_mfma_scale_f32_16x16x128_f8f6f4 v[52:55], v[136:143], v[194:201], v[52:55], v254, v254 op_sel_hi:[0,0,0]
	v_mfma_scale_f32_16x16x128_f8f6f4 v[48:51], v[128:135], v[194:201], v[48:51], v254, v254 op_sel_hi:[0,0,0]
	v_mfma_scale_f32_16x16x128_f8f6f4 v[36:39], v[136:143], v[202:209], v[36:39], v254, v254 op_sel_hi:[0,0,0]
	v_mfma_scale_f32_16x16x128_f8f6f4 v[32:35], v[128:135], v[202:209], v[32:35], v254, v254 op_sel_hi:[0,0,0]
	v_mfma_scale_f32_16x16x128_f8f6f4 v[20:23], v[136:143], v[210:217], v[20:23], v254, v254 op_sel_hi:[0,0,0]
	v_mfma_scale_f32_16x16x128_f8f6f4 v[16:19], v[128:135], v[210:217], v[16:19], v254, v254 op_sel_hi:[0,0,0]
	v_mfma_scale_f32_16x16x128_f8f6f4 v[4:7], v[136:143], v[218:225], v[4:7], v254, v254 op_sel_hi:[0,0,0]
	v_mfma_scale_f32_16x16x128_f8f6f4 v[0:3], v[128:135], v[218:225], v[0:3], v254, v254 op_sel_hi:[0,0,0]
	s_setprio 0
	s_barrier
	s_add_i32 s53, s53, 2
	s_add_u32 s28, s28, 0x100
	s_addc_u32 s29, s29, 0
	s_add_u32 s50, s50, 0x100
	s_addc_u32 s51, s51, 0
	s_cmp_gt_u32 s53, 13
	s_cbranch_scc0 .LBB0_208
	s_and_b64 vcc, exec, s[14:15]
	s_cbranch_vccz .LBB0_211
	s_barrier

; #define PG8_STAGE(bufoff, gbase, voff) do { _Pragma("unroll") for (int _i = 0; _i < 2; ++_i) \
;         __builtin_amdgcn_global_load_lds((const unsigned*)((const char*)(gbase) + (voff)[_i]), (LAS unsigned*)(lds + (bufoff) + ldsw + _i * 8192), 16, 0, 0); } while (0)
; #define PG8_LDA(dst, b, h) do { _Pragma("unroll") for (int m = 0; m < 4; ++m) _Pragma("unroll") for (int k = 0; k < 2; ++k) dst[m][k] = *(const LAS bf16x8*)(lds + PG8_SA(b, h) + aoff + m * 2048 + k * 1024); } while (0)
; #define PG8_LDB(dst, b, h) do { _Pragma("unroll") for (int n = 0; n < 2; ++n) _Pragma("unroll") for (int k = 0; k < 2; ++k) dst[n][k] = *(const LAS bf16x8*)(lds + PG8_SB(b, h) + boff + n * 2048 + k * 1024); } while (0)
; #define PG8_WAIT_V(n) asm volatile("s_waitcnt vmcnt(" #n ")" ::: "memory")
; #define PG8_WAIT_L(n) asm volatile("s_waitcnt lgkmcnt(" #n ")" ::: "memory")
; #define PG8_BAR __builtin_amdgcn_s_barrier()
; #define PG8_SCHED __builtin_amdgcn_sched_barrier(0)
; template <class Epi, class Sched, bool F8 = false>
; __device__ __forceinline__ void gemm_phase(LAS unsigned char* lds, const Gemm g, const Sched& S, const Epi& E) {
;     ...
;         for (int t = 0; t < nt; t += 2) {
;             const bool last = (t == nt - 2);
;             const char* a1 = cA + (size_t)(t + 1) * kstep;
;             const char* a2 = last ? nA : cA + (size_t)(t + 2) * kstep; const char* b2 = last ? nB : cB + (size_t)(t + 2) * kstep;
;             const char* a3 = a2 + kstep; const char* b3 = b2 + kstep;
;             PG8_LDB(B0, 0, 0); PG8_LDB(B1, 0, 1); PG8_SCHED; PG8_LDA(At, 0, 0); PG8_STAGE(PG8_SA(1, 1), a1 + hstepA, voffA);
;             PG8_WAIT_V(8); PG8_WAIT_L(0); PG8_BAR; PG8_MMA(0, 0, At, B0); PG8_MMA(0, 1, At, B1); PG8_BAR; PG8_SCHED;
;             PG8_LDA(At, 0, 1); PG8_STAGE(PG8_SB(0, 0), b2, voffB); PG8_STAGE(PG8_SB(0, 1), b2 + hstepB, voffB); PG8_STAGE(PG8_SA(0, 0), a2, voffA);
;             PG8_WAIT_V(8); PG8_WAIT_L(0); PG8_BAR; PG8_MMA(1, 0, At, B0); PG8_MMA(1, 1, At, B1); PG8_BAR; PG8_SCHED;
.LBB0_356:
	ds_read_b128 v[168:171], v158
	ds_read_b128 v[172:175], v158 offset:1024
	ds_read_b128 v[176:179], v158 offset:2048
	ds_read_b128 v[180:183], v158 offset:3072
	ds_read_b128 v[184:187], v160
	ds_read_b128 v[192:195], v160 offset:1024
	ds_read_b128 v[196:199], v160 offset:2048
	ds_read_b128 v[200:203], v160 offset:3072
	s_add_u32 s8, s30, 0x100
	s_addc_u32 s9, s31, 0
	s_cmp_eq_u32 s59, 4
	s_cselect_b32 s37, s25, s9
	s_cselect_b32 s36, s24, s8
	s_cselect_b32 s35, s10, s58
	s_cselect_b32 s34, s21, s29
	s_add_i32 m0, s40, 0xc000
	ds_read_b128 v[204:207], v159
	ds_read_b128 v[208:211], v159 offset:1024
	ds_read_b128 v[212:215], v159 offset:2048
	ds_read_b128 v[216:219], v159 offset:3072
	ds_read_b128 v[220:223], v159 offset:4096
	ds_read_b128 v[224:227], v159 offset:5120
	ds_read_b128 v[228:231], v159 offset:6144
	ds_read_b128 v[232:235], v159 offset:7168
	global_load_lds_dwordx4 v144, s[30:31]
	s_add_i32 m0, s40, 0xe000
	s_nop 0
	global_load_lds_dwordx4 v146, s[30:31]
	s_waitcnt vmcnt(8)
	s_waitcnt lgkmcnt(0)
	s_barrier
	s_setprio 1
	s_waitcnt lgkmcnt(0)
	v_mfma_f32_16x16x32_bf16 v[124:127], v[168:171], v[204:207], v[124:127]
	v_mfma_f32_16x16x32_bf16 v[120:123], v[176:179], v[204:207], v[120:123]
	v_mfma_f32_16x16x32_bf16 v[108:111], v[168:171], v[212:215], v[108:111]
	v_mfma_f32_16x16x32_bf16 v[104:107], v[176:179], v[212:215], v[104:107]
	v_mfma_f32_16x16x32_bf16 v[92:95], v[168:171], v[220:223], v[92:95]
	v_mfma_f32_16x16x32_bf16 v[88:91], v[176:179], v[220:223], v[88:91]
	v_mfma_f32_16x16x32_bf16 v[76:79], v[168:171], v[228:231], v[76:79]
	v_mfma_f32_16x16x32_bf16 v[72:75], v[176:179], v[228:231], v[72:75]
	v_mfma_f32_16x16x32_bf16 v[124:127], v[172:175], v[208:211], v[124:127]
	v_mfma_f32_16x16x32_bf16 v[120:123], v[180:183], v[208:211], v[120:123]
	v_mfma_f32_16x16x32_bf16 v[108:111], v[172:175], v[216:219], v[108:111]
	v_mfma_f32_16x16x32_bf16 v[104:107], v[180:183], v[216:219], v[104:107]
	v_mfma_f32_16x16x32_bf16 v[92:95], v[172:175], v[224:227], v[92:95]
	v_mfma_f32_16x16x32_bf16 v[88:91], v[180:183], v[224:227], v[88:91]
	v_mfma_f32_16x16x32_bf16 v[76:79], v[172:175], v[232:235], v[76:79]
	v_mfma_f32_16x16x32_bf16 v[72:75], v[180:183], v[232:235], v[72:75]
	s_setprio 0
	s_setprio 1
	v_mfma_f32_16x16x32_bf16 v[116:119], v[184:187], v[204:207], v[116:119]
	v_mfma_f32_16x16x32_bf16 v[112:115], v[196:199], v[204:207], v[112:115]
	v_mfma_f32_16x16x32_bf16 v[100:103], v[184:187], v[212:215], v[100:103]
	v_mfma_f32_16x16x32_bf16 v[96:99], v[196:199], v[212:215], v[96:99]
	v_mfma_f32_16x16x32_bf16 v[84:87], v[184:187], v[220:223], v[84:87]
	v_mfma_f32_16x16x32_bf16 v[80:83], v[196:199], v[220:223], v[80:83]
	v_mfma_f32_16x16x32_bf16 v[68:71], v[184:187], v[228:231], v[68:71]
	v_mfma_f32_16x16x32_bf16 v[64:67], v[196:199], v[228:231], v[64:67]
	v_mfma_f32_16x16x32_bf16 v[116:119], v[192:195], v[208:211], v[116:119]
	v_mfma_f32_16x16x32_bf16 v[112:115], v[200:203], v[208:211], v[112:115]
	v_mfma_f32_16x16x32_bf16 v[100:103], v[192:195], v[216:219], v[100:103]
	v_mfma_f32_16x16x32_bf16 v[96:99], v[200:203], v[216:219], v[96:99]
	v_mfma_f32_16x16x32_bf16 v[84:87], v[192:195], v[224:227], v[84:87]
	v_mfma_f32_16x16x32_bf16 v[80:83], v[200:203], v[224:227], v[80:83]
	v_mfma_f32_16x16x32_bf16 v[68:71], v[192:195], v[232:235], v[68:71]
	v_mfma_f32_16x16x32_bf16 v[64:67], v[200:203], v[232:235], v[64:67]
	s_setprio 0
	s_barrier
	s_add_i32 s30, s50, s39
	v_lshl_add_u64 v[152:153], s[34:35], 0, v[130:131]
	s_mov_b32 m0, s30
	ds_read_b128 v[204:207], v159 offset:16384
	ds_read_b128 v[208:211], v159 offset:17408
	ds_read_b128 v[212:215], v159 offset:18432
	ds_read_b128 v[216:219], v159 offset:19456
	ds_read_b128 v[220:223], v159 offset:20480
	ds_read_b128 v[224:227], v159 offset:21504
	ds_read_b128 v[228:231], v159 offset:22528
	ds_read_b128 v[232:235], v159 offset:23552
	global_load_lds_dwordx4 v[152:153], off
	s_add_i32 m0, s30, 0x2000
	s_add_u32 s30, s34, 0x20000
	v_lshl_add_u64 v[188:189], s[34:35], 0, v[134:135]
	s_addc_u32 s31, s35, 0
	s_add_i32 s72, s51, s39
	global_load_lds_dwordx4 v[188:189], off
	s_mov_b32 m0, s72
	v_lshl_add_u64 v[238:239], s[36:37], 0, v[132:133]
	global_load_lds_dwordx4 v130, s[30:31]
	s_add_i32 m0, s72, 0x2000
	s_nop 0
	global_load_lds_dwordx4 v134, s[30:31]
	v_lshl_add_u64 v[236:237], s[36:37], 0, v[128:129]
	s_mov_b32 m0, s40
	s_nop 0
	global_load_lds_dwordx4 v[236:237], off
	s_mov_b32 m0, s41
	s_nop 0
	global_load_lds_dwordx4 v[238:239], off
	s_waitcnt vmcnt(8)
	s_waitcnt lgkmcnt(0)
	s_barrier
; #define PG8_STAGE(bufoff, gbase, voff) do { _Pragma("unroll") for (int _i = 0; _i < 2; ++_i) \
;         __builtin_amdgcn_global_load_lds((const unsigned*)((const char*)(gbase) + (voff)[_i]), (LAS unsigned*)(lds + (bufoff) + ldsw + _i * 8192), 16, 0, 0); } while (0)
; #define PG8_LDA(dst, b, h) do { _Pragma("unroll") for (int m = 0; m < 4; ++m) _Pragma("unroll") for (int k = 0; k < 2; ++k) dst[m][k] = *(const LAS bf16x8*)(lds + PG8_SA(b, h) + aoff + m * 2048 + k * 1024); } while (0)
; #define PG8_LDB(dst, b, h) do { _Pragma("unroll") for (int n = 0; n < 2; ++n) _Pragma("unroll") for (int k = 0; k < 2; ++k) dst[n][k] = *(const LAS bf16x8*)(lds + PG8_SB(b, h) + boff + n * 2048 + k * 1024); } while (0)
; #define PG8_WAIT_V(n) asm volatile("s_waitcnt vmcnt(" #n ")" ::: "memory")
; #define PG8_WAIT_L(n) asm volatile("s_waitcnt lgkmcnt(" #n ")" ::: "memory")
; #define PG8_BAR __builtin_amdgcn_s_barrier()
; #define PG8_SCHED __builtin_amdgcn_sched_barrier(0)
; template <class Epi, class Sched, bool F8 = false>
; __device__ __forceinline__ void gemm_phase(LAS unsigned char* lds, const Gemm g, const Sched& S, const Epi& E) {
;     ...
;             PG8_WAIT_V(8); PG8_WAIT_L(0); PG8_BAR; PG8_MMA(1, 0, At, B0); PG8_MMA(1, 1, At, B1); PG8_BAR; PG8_SCHED;
;             PG8_LDB(B0, 1, 0); PG8_LDB(B1, 1, 1); PG8_SCHED; PG8_LDA(At, 1, 0); PG8_STAGE(PG8_SA(0, 1), a2 + hstepA, voffA);
;             PG8_WAIT_V(8); PG8_WAIT_L(0); PG8_BAR; PG8_MMA(0, 0, At, B0); PG8_MMA(0, 1, At, B1); PG8_BAR; PG8_SCHED;
	s_setprio 1
	s_waitcnt lgkmcnt(0)
	v_mfma_f32_16x16x32_bf16 v[60:63], v[168:171], v[204:207], v[60:63]
	v_mfma_f32_16x16x32_bf16 v[56:59], v[176:179], v[204:207], v[56:59]
	v_mfma_f32_16x16x32_bf16 v[44:47], v[168:171], v[212:215], v[44:47]
	v_mfma_f32_16x16x32_bf16 v[40:43], v[176:179], v[212:215], v[40:43]
	v_mfma_f32_16x16x32_bf16 v[28:31], v[168:171], v[220:223], v[28:31]
	v_mfma_f32_16x16x32_bf16 v[24:27], v[176:179], v[220:223], v[24:27]
	v_mfma_f32_16x16x32_bf16 v[12:15], v[168:171], v[228:231], v[12:15]
	v_mfma_f32_16x16x32_bf16 v[8:11], v[176:179], v[228:231], v[8:11]
	v_mfma_f32_16x16x32_bf16 v[60:63], v[172:175], v[208:211], v[60:63]
	v_mfma_f32_16x16x32_bf16 v[56:59], v[180:183], v[208:211], v[56:59]
	v_mfma_f32_16x16x32_bf16 v[44:47], v[172:175], v[216:219], v[44:47]
	v_mfma_f32_16x16x32_bf16 v[40:43], v[180:183], v[216:219], v[40:43]
	v_mfma_f32_16x16x32_bf16 v[28:31], v[172:175], v[224:227], v[28:31]
	v_mfma_f32_16x16x32_bf16 v[24:27], v[180:183], v[224:227], v[24:27]
	v_mfma_f32_16x16x32_bf16 v[12:15], v[172:175], v[232:235], v[12:15]
	v_mfma_f32_16x16x32_bf16 v[8:11], v[180:183], v[232:235], v[8:11]
	s_setprio 0
	s_setprio 1
	v_mfma_f32_16x16x32_bf16 v[52:55], v[184:187], v[204:207], v[52:55]
	v_mfma_f32_16x16x32_bf16 v[48:51], v[196:199], v[204:207], v[48:51]
	v_mfma_f32_16x16x32_bf16 v[36:39], v[184:187], v[212:215], v[36:39]
	v_mfma_f32_16x16x32_bf16 v[32:35], v[196:199], v[212:215], v[32:35]
	v_mfma_f32_16x16x32_bf16 v[20:23], v[184:187], v[220:223], v[20:23]
	v_mfma_f32_16x16x32_bf16 v[16:19], v[196:199], v[220:223], v[16:19]
	v_mfma_f32_16x16x32_bf16 v[4:7], v[184:187], v[228:231], v[4:7]
	v_mfma_f32_16x16x32_bf16 v[0:3], v[196:199], v[228:231], v[0:3]
	v_mfma_f32_16x16x32_bf16 v[52:55], v[192:195], v[208:211], v[52:55]
	v_mfma_f32_16x16x32_bf16 v[48:51], v[200:203], v[208:211], v[48:51]
	v_mfma_f32_16x16x32_bf16 v[36:39], v[192:195], v[216:219], v[36:39]
	v_mfma_f32_16x16x32_bf16 v[32:35], v[200:203], v[216:219], v[32:35]
	v_mfma_f32_16x16x32_bf16 v[20:23], v[192:195], v[224:227], v[20:23]
	v_mfma_f32_16x16x32_bf16 v[16:19], v[200:203], v[224:227], v[16:19]
	v_mfma_f32_16x16x32_bf16 v[4:7], v[192:195], v[232:235], v[4:7]
	v_mfma_f32_16x16x32_bf16 v[0:3], v[200:203], v[232:235], v[0:3]
	s_setprio 0
	s_barrier
	s_add_i32 s72, 0, 0x18000
	v_add_u32_e32 v154, s72, v156
	s_add_i32 s73, 0, 0x1c000
	ds_read_b128 v[168:171], v154
	ds_read_b128 v[172:175], v154 offset:1024
	ds_read_b128 v[176:179], v154 offset:2048
	ds_read_b128 v[180:183], v154 offset:3072
	v_add_u32_e32 v154, s73, v156
	ds_read_b128 v[184:187], v154
	ds_read_b128 v[192:195], v154 offset:1024
	ds_read_b128 v[196:199], v154 offset:2048
	ds_read_b128 v[200:203], v154 offset:3072
	s_add_u32 s30, s36, 0xc0000
	s_addc_u32 s31, s37, 0
	s_mov_b32 m0, s42
	ds_read_b128 v[204:207], v159 offset:32768
	ds_read_b128 v[208:211], v159 offset:33792
	ds_read_b128 v[212:215], v159 offset:34816
	ds_read_b128 v[216:219], v159 offset:35840
	ds_read_b128 v[220:223], v159 offset:36864
	ds_read_b128 v[224:227], v159 offset:37888
	ds_read_b128 v[228:231], v159 offset:38912
	ds_read_b128 v[232:235], v159 offset:39936
	global_load_lds_dwordx4 v128, s[30:31]
	s_mov_b32 m0, s43
	s_nop 0
	global_load_lds_dwordx4 v132, s[30:31]
	s_waitcnt vmcnt(8)
	s_waitcnt lgkmcnt(0)
	s_barrier
	s_setprio 1
	s_waitcnt lgkmcnt(0)
	v_mfma_f32_16x16x32_bf16 v[124:127], v[168:171], v[204:207], v[124:127]
	v_mfma_f32_16x16x32_bf16 v[120:123], v[176:179], v[204:207], v[120:123]
	v_mfma_f32_16x16x32_bf16 v[108:111], v[168:171], v[212:215], v[108:111]
	v_mfma_f32_16x16x32_bf16 v[104:107], v[176:179], v[212:215], v[104:107]
	v_mfma_f32_16x16x32_bf16 v[92:95], v[168:171], v[220:223], v[92:95]
	v_mfma_f32_16x16x32_bf16 v[88:91], v[176:179], v[220:223], v[88:91]
	v_mfma_f32_16x16x32_bf16 v[76:79], v[168:171], v[228:231], v[76:79]
	v_mfma_f32_16x16x32_bf16 v[72:75], v[176:179], v[228:231], v[72:75]
	v_mfma_f32_16x16x32_bf16 v[124:127], v[172:175], v[208:211], v[124:127]
	v_mfma_f32_16x16x32_bf16 v[120:123], v[180:183], v[208:211], v[120:123]
	v_mfma_f32_16x16x32_bf16 v[108:111], v[172:175], v[216:219], v[108:111]
	v_mfma_f32_16x16x32_bf16 v[104:107], v[180:183], v[216:219], v[104:107]
	v_mfma_f32_16x16x32_bf16 v[92:95], v[172:175], v[224:227], v[92:95]
	v_mfma_f32_16x16x32_bf16 v[88:91], v[180:183], v[224:227], v[88:91]
	v_mfma_f32_16x16x32_bf16 v[76:79], v[172:175], v[232:235], v[76:79]
	v_mfma_f32_16x16x32_bf16 v[72:75], v[180:183], v[232:235], v[72:75]
	s_setprio 0
	s_setprio 1
	v_mfma_f32_16x16x32_bf16 v[116:119], v[184:187], v[204:207], v[116:119]
	v_mfma_f32_16x16x32_bf16 v[112:115], v[196:199], v[204:207], v[112:115]
	v_mfma_f32_16x16x32_bf16 v[100:103], v[184:187], v[212:215], v[100:103]
	v_mfma_f32_16x16x32_bf16 v[96:99], v[196:199], v[212:215], v[96:99]
	v_mfma_f32_16x16x32_bf16 v[84:87], v[184:187], v[220:223], v[84:87]
	v_mfma_f32_16x16x32_bf16 v[80:83], v[196:199], v[220:223], v[80:83]
	v_mfma_f32_16x16x32_bf16 v[68:71], v[184:187], v[228:231], v[68:71]
	v_mfma_f32_16x16x32_bf16 v[64:67], v[196:199], v[228:231], v[64:67]
	v_mfma_f32_16x16x32_bf16 v[116:119], v[192:195], v[208:211], v[116:119]
	v_mfma_f32_16x16x32_bf16 v[112:115], v[200:203], v[208:211], v[112:115]
	v_mfma_f32_16x16x32_bf16 v[100:103], v[192:195], v[216:219], v[100:103]
	v_mfma_f32_16x16x32_bf16 v[96:99], v[200:203], v[216:219], v[96:99]
	v_mfma_f32_16x16x32_bf16 v[84:87], v[192:195], v[224:227], v[84:87]
	v_mfma_f32_16x16x32_bf16 v[80:83], v[200:203], v[224:227], v[80:83]
	v_mfma_f32_16x16x32_bf16 v[68:71], v[192:195], v[232:235], v[68:71]
	v_mfma_f32_16x16x32_bf16 v[64:67], v[200:203], v[232:235], v[64:67]
	s_setprio 0
	s_barrier
; #define PG8_STAGE(bufoff, gbase, voff) do { _Pragma("unroll") for (int _i = 0; _i < 2; ++_i) \
;         __builtin_amdgcn_global_load_lds((const unsigned*)((const char*)(gbase) + (voff)[_i]), (LAS unsigned*)(lds + (bufoff) + ldsw + _i * 8192), 16, 0, 0); } while (0)
; #define PG8_LDA(dst, b, h) do { _Pragma("unroll") for (int m = 0; m < 4; ++m) _Pragma("unroll") for (int k = 0; k < 2; ++k) dst[m][k] = *(const LAS bf16x8*)(lds + PG8_SA(b, h) + aoff + m * 2048 + k * 1024); } while (0)
; #define PG8_WAIT_V(n) asm volatile("s_waitcnt vmcnt(" #n ")" ::: "memory")
; #define PG8_WAIT_L(n) asm volatile("s_waitcnt lgkmcnt(" #n ")" ::: "memory")
; #define PG8_BAR __builtin_amdgcn_s_barrier()
; #define PG8_SCHED __builtin_amdgcn_sched_barrier(0)
; template <class Epi, class Sched, bool F8 = false>
; __device__ __forceinline__ void gemm_phase(LAS unsigned char* lds, const Gemm g, const Sched& S, const Epi& E) {
;     ...
;             PG8_LDA(At, 1, 1); PG8_STAGE(PG8_SB(1, 0), b3, voffB); PG8_STAGE(PG8_SB(1, 1), b3 + hstepB, voffB); PG8_STAGE(PG8_SA(1, 0), a3, voffA);
;             PG8_WAIT_V(8); PG8_WAIT_L(0); PG8_BAR; PG8_MMA(1, 0, At, B0); PG8_MMA(1, 1, At, B1); PG8_BAR; PG8_SCHED;
;         }
;         if (wr == 0) PG8_BAR;
	s_add_i32 s30, s72, s39
	s_add_i32 m0, s30, 0xffffff80
	ds_read_b128 v[204:207], v159 offset:49152
	ds_read_b128 v[208:211], v159 offset:50176
	ds_read_b128 v[212:215], v159 offset:51200
	ds_read_b128 v[216:219], v159 offset:52224
	ds_read_b128 v[220:223], v159 offset:53248
	ds_read_b128 v[224:227], v159 offset:54272
	ds_read_b128 v[228:231], v159 offset:55296
	ds_read_b128 v[232:235], v159 offset:56320
	global_load_lds_dwordx4 v[152:153], off offset:128
	s_add_i32 m0, s30, 0x1f80
	s_add_u32 s30, s34, 0x20080
	s_addc_u32 s31, s35, 0
	s_add_i32 s34, s73, s39
	global_load_lds_dwordx4 v[188:189], off offset:128
	s_mov_b32 m0, s34
	s_nop 0
	global_load_lds_dwordx4 v130, s[30:31]
	s_add_i32 m0, s34, 0x2000
	s_nop 0
	global_load_lds_dwordx4 v134, s[30:31]
	s_add_i32 m0, s45, 0xffffff80
	s_nop 0
	global_load_lds_dwordx4 v[236:237], off offset:128
	s_add_i32 m0, s47, 0xffffff80
	s_nop 0
	global_load_lds_dwordx4 v[238:239], off offset:128
	s_waitcnt vmcnt(8)
	s_waitcnt lgkmcnt(0)
	s_barrier
	s_setprio 1
	s_waitcnt lgkmcnt(0)
	v_mfma_f32_16x16x32_bf16 v[60:63], v[168:171], v[204:207], v[60:63]
	v_mfma_f32_16x16x32_bf16 v[56:59], v[176:179], v[204:207], v[56:59]
	v_mfma_f32_16x16x32_bf16 v[44:47], v[168:171], v[212:215], v[44:47]
	v_mfma_f32_16x16x32_bf16 v[40:43], v[176:179], v[212:215], v[40:43]
	v_mfma_f32_16x16x32_bf16 v[28:31], v[168:171], v[220:223], v[28:31]
	v_mfma_f32_16x16x32_bf16 v[24:27], v[176:179], v[220:223], v[24:27]
	v_mfma_f32_16x16x32_bf16 v[12:15], v[168:171], v[228:231], v[12:15]
	v_mfma_f32_16x16x32_bf16 v[8:11], v[176:179], v[228:231], v[8:11]
	v_mfma_f32_16x16x32_bf16 v[60:63], v[172:175], v[208:211], v[60:63]
	v_mfma_f32_16x16x32_bf16 v[56:59], v[180:183], v[208:211], v[56:59]
	v_mfma_f32_16x16x32_bf16 v[44:47], v[172:175], v[216:219], v[44:47]
	v_mfma_f32_16x16x32_bf16 v[40:43], v[180:183], v[216:219], v[40:43]
	v_mfma_f32_16x16x32_bf16 v[28:31], v[172:175], v[224:227], v[28:31]
	v_mfma_f32_16x16x32_bf16 v[24:27], v[180:183], v[224:227], v[24:27]
	v_mfma_f32_16x16x32_bf16 v[12:15], v[172:175], v[232:235], v[12:15]
	v_mfma_f32_16x16x32_bf16 v[8:11], v[180:183], v[232:235], v[8:11]
	s_setprio 0
	s_setprio 1
	v_mfma_f32_16x16x32_bf16 v[52:55], v[184:187], v[204:207], v[52:55]
	v_mfma_f32_16x16x32_bf16 v[48:51], v[196:199], v[204:207], v[48:51]
	v_mfma_f32_16x16x32_bf16 v[36:39], v[184:187], v[212:215], v[36:39]
	v_mfma_f32_16x16x32_bf16 v[32:35], v[196:199], v[212:215], v[32:35]
	v_mfma_f32_16x16x32_bf16 v[20:23], v[184:187], v[220:223], v[20:23]
	v_mfma_f32_16x16x32_bf16 v[16:19], v[196:199], v[220:223], v[16:19]
	v_mfma_f32_16x16x32_bf16 v[4:7], v[184:187], v[228:231], v[4:7]
	v_mfma_f32_16x16x32_bf16 v[0:3], v[196:199], v[228:231], v[0:3]
	v_mfma_f32_16x16x32_bf16 v[52:55], v[192:195], v[208:211], v[52:55]
	v_mfma_f32_16x16x32_bf16 v[48:51], v[200:203], v[208:211], v[48:51]
	v_mfma_f32_16x16x32_bf16 v[36:39], v[192:195], v[216:219], v[36:39]
	v_mfma_f32_16x16x32_bf16 v[32:35], v[200:203], v[216:219], v[32:35]
	v_mfma_f32_16x16x32_bf16 v[20:23], v[192:195], v[224:227], v[20:23]
	v_mfma_f32_16x16x32_bf16 v[16:19], v[200:203], v[224:227], v[16:19]
	v_mfma_f32_16x16x32_bf16 v[4:7], v[192:195], v[232:235], v[4:7]
	v_mfma_f32_16x16x32_bf16 v[0:3], v[200:203], v[232:235], v[0:3]
	s_setprio 0
	s_barrier
	s_add_i32 s59, s59, 2
	s_add_u32 s29, s29, 0x100
	s_addc_u32 s58, s58, 0
	s_cmp_gt_u32 s59, 5
	s_mov_b64 s[30:31], s[8:9]
	s_cbranch_scc0 .LBB0_356
	s_and_b64 vcc, exec, s[18:19]
	s_cbranch_vccz .LBB0_359
	s_barrier

; #define PG8_STAGE(bufoff, gbase, voff) do { _Pragma("unroll") for (int _i = 0; _i < 2; ++_i) \
;         __builtin_amdgcn_global_load_lds((const unsigned*)((const char*)(gbase) + (voff)[_i]), (LAS unsigned*)(lds + (bufoff) + ldsw + _i * 8192), 16, 0, 0); } while (0)
; #define PG8_LDA(dst, b, h) do { _Pragma("unroll") for (int m = 0; m < 4; ++m) _Pragma("unroll") for (int k = 0; k < 2; ++k) dst[m][k] = *(const LAS bf16x8*)(lds + PG8_SA(b, h) + aoff + m * 2048 + k * 1024); } while (0)
; #define PG8_LDB(dst, b, h) do { _Pragma("unroll") for (int n = 0; n < 2; ++n) _Pragma("unroll") for (int k = 0; k < 2; ++k) dst[n][k] = *(const LAS bf16x8*)(lds + PG8_SB(b, h) + boff + n * 2048 + k * 1024); } while (0)
; #define PG8_WAIT_V(n) asm volatile("s_waitcnt vmcnt(" #n ")" ::: "memory")
; #define PG8_WAIT_L(n) asm volatile("s_waitcnt lgkmcnt(" #n ")" ::: "memory")
; #define PG8_BAR __builtin_amdgcn_s_barrier()
; #define PG8_SCHED __builtin_amdgcn_sched_barrier(0)
; template <class Epi, class Sched, bool F8 = false>
; __device__ __forceinline__ void gemm_phase(LAS unsigned char* lds, const Gemm g, const Sched& S, const Epi& E) {
;     ...
;         const char* nA = has_next ? (const char*)g.A + (size_t)nxt.pm * tstepA + nxt.aoff : cA; const char* nB = has_next ? (const char*)g.Bt + (size_t)nxt.pn * tstepB + nxt.boff : cB;
;         const int nt = cur.nt ? cur.nt : K / BK;
;         for (int t = 0; t < nt; t += 2) {
;             const bool last = (t == nt - 2);
;             const char* a1 = cA + (size_t)(t + 1) * kstep;
;             const char* a2 = last ? nA : cA + (size_t)(t + 2) * kstep; const char* b2 = last ? nB : cB + (size_t)(t + 2) * kstep;
;             const char* a3 = a2 + kstep; const char* b3 = b2 + kstep;
;             PG8_LDB(B0, 0, 0); PG8_LDB(B1, 0, 1); PG8_SCHED; PG8_LDA(At, 0, 0); PG8_STAGE(PG8_SA(1, 1), a1 + hstepA, voffA);
;             PG8_WAIT_V(8); PG8_WAIT_L(0); PG8_BAR; PG8_MMA(0, 0, At, B0); PG8_MMA(0, 1, At, B1); PG8_BAR; PG8_SCHED;
;             PG8_LDA(At, 0, 1); PG8_STAGE(PG8_SB(0, 0), b2, voffB); PG8_STAGE(PG8_SB(0, 1), b2 + hstepB, voffB); PG8_STAGE(PG8_SA(0, 0), a2, voffA);
;             PG8_WAIT_V(8); PG8_WAIT_L(0); PG8_BAR; PG8_MMA(1, 0, At, B0); PG8_MMA(1, 1, At, B1); PG8_BAR; PG8_SCHED;
.LBB0_753:
	v_add_u32_e32 v140, s48, v197
	v_add_u32_e32 v156, s91, v197
	ds_read_b128 v[128:131], v140
	ds_read_b128 v[132:135], v140 offset:1024
	ds_read_b128 v[136:139], v140 offset:2048
	ds_read_b128 v[140:143], v140 offset:3072
	ds_read_b128 v[144:147], v156
	ds_read_b128 v[148:151], v156 offset:1024
	ds_read_b128 v[152:155], v156 offset:2048
	ds_read_b128 v[156:159], v156 offset:3072
	s_add_i32 s80, s34, 2
	s_add_u32 s35, s30, 0xfff80080
	s_addc_u32 s36, s31, -1
	s_cmp_eq_u32 s77, s34
	s_cselect_b32 s34, s76, s78
	s_cselect_b32 s37, s25, s36
	s_cselect_b32 s36, s75, s35
	s_cselect_b32 s35, s21, s79
	s_add_i32 m0, s40, 0xc000
	ds_read_b128 v[160:163], v199
	ds_read_b128 v[164:167], v199 offset:1024
	ds_read_b128 v[168:171], v199 offset:2048
	ds_read_b128 v[172:175], v199 offset:3072
	ds_read_b128 v[200:203], v199 offset:4096
	ds_read_b128 v[204:207], v199 offset:5120
	ds_read_b128 v[208:211], v199 offset:6144
	ds_read_b128 v[212:215], v199 offset:7168
	global_load_lds_dwordx4 v186, s[30:31]
	s_add_i32 m0, s40, 0xe000
	s_nop 0
	global_load_lds_dwordx4 v188, s[30:31]
	s_waitcnt vmcnt(8)
	s_waitcnt lgkmcnt(0)
	s_barrier
	s_setprio 1
	s_waitcnt lgkmcnt(0)
	v_mfma_f32_16x16x32_bf16 v[124:127], v[128:131], v[160:163], v[124:127]
	v_mfma_f32_16x16x32_bf16 v[120:123], v[136:139], v[160:163], v[120:123]
	v_mfma_f32_16x16x32_bf16 v[116:119], v[128:131], v[168:171], v[116:119]
	v_mfma_f32_16x16x32_bf16 v[112:115], v[136:139], v[168:171], v[112:115]
	v_mfma_f32_16x16x32_bf16 v[108:111], v[128:131], v[200:203], v[108:111]
	v_mfma_f32_16x16x32_bf16 v[104:107], v[136:139], v[200:203], v[104:107]
	v_mfma_f32_16x16x32_bf16 v[100:103], v[128:131], v[208:211], v[100:103]
	v_mfma_f32_16x16x32_bf16 v[96:99], v[136:139], v[208:211], v[96:99]
	v_mfma_f32_16x16x32_bf16 v[124:127], v[132:135], v[164:167], v[124:127]
	v_mfma_f32_16x16x32_bf16 v[120:123], v[140:143], v[164:167], v[120:123]
	v_mfma_f32_16x16x32_bf16 v[116:119], v[132:135], v[172:175], v[116:119]
	v_mfma_f32_16x16x32_bf16 v[112:115], v[140:143], v[172:175], v[112:115]
	v_mfma_f32_16x16x32_bf16 v[108:111], v[132:135], v[204:207], v[108:111]
	v_mfma_f32_16x16x32_bf16 v[104:107], v[140:143], v[204:207], v[104:107]
	v_mfma_f32_16x16x32_bf16 v[100:103], v[132:135], v[212:215], v[100:103]
	v_mfma_f32_16x16x32_bf16 v[96:99], v[140:143], v[212:215], v[96:99]
	s_setprio 0
	s_setprio 1
	v_mfma_f32_16x16x32_bf16 v[92:95], v[144:147], v[160:163], v[92:95]
	v_mfma_f32_16x16x32_bf16 v[88:91], v[152:155], v[160:163], v[88:91]
	v_mfma_f32_16x16x32_bf16 v[84:87], v[144:147], v[168:171], v[84:87]
	v_mfma_f32_16x16x32_bf16 v[80:83], v[152:155], v[168:171], v[80:83]
	v_mfma_f32_16x16x32_bf16 v[76:79], v[144:147], v[200:203], v[76:79]
	v_mfma_f32_16x16x32_bf16 v[72:75], v[152:155], v[200:203], v[72:75]
	v_mfma_f32_16x16x32_bf16 v[68:71], v[144:147], v[208:211], v[68:71]
	v_mfma_f32_16x16x32_bf16 v[64:67], v[152:155], v[208:211], v[64:67]
	v_mfma_f32_16x16x32_bf16 v[92:95], v[148:151], v[164:167], v[92:95]
	v_mfma_f32_16x16x32_bf16 v[88:91], v[156:159], v[164:167], v[88:91]
	v_mfma_f32_16x16x32_bf16 v[84:87], v[148:151], v[172:175], v[84:87]
	v_mfma_f32_16x16x32_bf16 v[80:83], v[156:159], v[172:175], v[80:83]
	v_mfma_f32_16x16x32_bf16 v[76:79], v[148:151], v[204:207], v[76:79]
	v_mfma_f32_16x16x32_bf16 v[72:75], v[156:159], v[204:207], v[72:75]
	v_mfma_f32_16x16x32_bf16 v[68:71], v[148:151], v[212:215], v[68:71]
	v_mfma_f32_16x16x32_bf16 v[64:67], v[156:159], v[212:215], v[64:67]
	s_setprio 0
	s_barrier
	s_add_i32 s81, s48, s38
	v_lshl_add_u64 v[216:217], s[34:35], 0, v[180:181]
	s_mov_b32 m0, s81
	ds_read_b128 v[160:163], v199 offset:16384
	ds_read_b128 v[164:167], v199 offset:17408
	ds_read_b128 v[168:171], v199 offset:18432
	ds_read_b128 v[172:175], v199 offset:19456
	ds_read_b128 v[200:203], v199 offset:20480
	ds_read_b128 v[204:207], v199 offset:21504
	ds_read_b128 v[208:211], v199 offset:22528
	ds_read_b128 v[212:215], v199 offset:23552
	global_load_lds_dwordx4 v[216:217], off
	s_add_i32 m0, s81, 0x2000
	s_add_u32 s82, s34, 0x80000
	v_lshl_add_u64 v[218:219], s[34:35], 0, v[176:177]
	s_addc_u32 s83, s35, 0
	s_add_i32 s81, s91, s38
	global_load_lds_dwordx4 v[218:219], off
	s_mov_b32 m0, s81
	v_lshl_add_u64 v[222:223], s[36:37], 0, v[178:179]
	global_load_lds_dwordx4 v180, s[82:83]
	s_add_i32 m0, s81, 0x2000
	s_nop 0
	global_load_lds_dwordx4 v176, s[82:83]
	v_lshl_add_u64 v[220:221], s[36:37], 0, v[182:183]
	s_mov_b32 m0, s40
	s_nop 0
	global_load_lds_dwordx4 v[220:221], off
	s_mov_b32 m0, s41
	s_nop 0
	global_load_lds_dwordx4 v[222:223], off
	s_waitcnt vmcnt(8)
	s_waitcnt lgkmcnt(0)
	s_barrier
; #define PG8_STAGE(bufoff, gbase, voff) do { _Pragma("unroll") for (int _i = 0; _i < 2; ++_i) \
;         __builtin_amdgcn_global_load_lds((const unsigned*)((const char*)(gbase) + (voff)[_i]), (LAS unsigned*)(lds + (bufoff) + ldsw + _i * 8192), 16, 0, 0); } while (0)
; #define PG8_LDA(dst, b, h) do { _Pragma("unroll") for (int m = 0; m < 4; ++m) _Pragma("unroll") for (int k = 0; k < 2; ++k) dst[m][k] = *(const LAS bf16x8*)(lds + PG8_SA(b, h) + aoff + m * 2048 + k * 1024); } while (0)
; #define PG8_LDB(dst, b, h) do { _Pragma("unroll") for (int n = 0; n < 2; ++n) _Pragma("unroll") for (int k = 0; k < 2; ++k) dst[n][k] = *(const LAS bf16x8*)(lds + PG8_SB(b, h) + boff + n * 2048 + k * 1024); } while (0)
; #define PG8_WAIT_V(n) asm volatile("s_waitcnt vmcnt(" #n ")" ::: "memory")
; #define PG8_WAIT_L(n) asm volatile("s_waitcnt lgkmcnt(" #n ")" ::: "memory")
; #define PG8_BAR __builtin_amdgcn_s_barrier()
; #define PG8_SCHED __builtin_amdgcn_sched_barrier(0)
; template <class Epi, class Sched, bool F8 = false>
; __device__ __forceinline__ void gemm_phase(LAS unsigned char* lds, const Gemm g, const Sched& S, const Epi& E) {
;     ...
;             PG8_WAIT_V(8); PG8_WAIT_L(0); PG8_BAR; PG8_MMA(1, 0, At, B0); PG8_MMA(1, 1, At, B1); PG8_BAR; PG8_SCHED;
;             PG8_LDB(B0, 1, 0); PG8_LDB(B1, 1, 1); PG8_SCHED; PG8_LDA(At, 1, 0); PG8_STAGE(PG8_SA(0, 1), a2 + hstepA, voffA);
;             PG8_WAIT_V(8); PG8_WAIT_L(0); PG8_BAR; PG8_MMA(0, 0, At, B0); PG8_MMA(0, 1, At, B1); PG8_BAR; PG8_SCHED;
	s_setprio 1
	s_waitcnt lgkmcnt(0)
	v_mfma_f32_16x16x32_bf16 v[60:63], v[128:131], v[160:163], v[60:63]
	v_mfma_f32_16x16x32_bf16 v[56:59], v[136:139], v[160:163], v[56:59]
	v_mfma_f32_16x16x32_bf16 v[52:55], v[128:131], v[168:171], v[52:55]
	v_mfma_f32_16x16x32_bf16 v[48:51], v[136:139], v[168:171], v[48:51]
	v_mfma_f32_16x16x32_bf16 v[44:47], v[128:131], v[200:203], v[44:47]
	v_mfma_f32_16x16x32_bf16 v[40:43], v[136:139], v[200:203], v[40:43]
	v_mfma_f32_16x16x32_bf16 v[36:39], v[128:131], v[208:211], v[36:39]
	v_mfma_f32_16x16x32_bf16 v[32:35], v[136:139], v[208:211], v[32:35]
	v_mfma_f32_16x16x32_bf16 v[60:63], v[132:135], v[164:167], v[60:63]
	v_mfma_f32_16x16x32_bf16 v[56:59], v[140:143], v[164:167], v[56:59]
	v_mfma_f32_16x16x32_bf16 v[52:55], v[132:135], v[172:175], v[52:55]
	v_mfma_f32_16x16x32_bf16 v[48:51], v[140:143], v[172:175], v[48:51]
	v_mfma_f32_16x16x32_bf16 v[44:47], v[132:135], v[204:207], v[44:47]
	v_mfma_f32_16x16x32_bf16 v[40:43], v[140:143], v[204:207], v[40:43]
	v_mfma_f32_16x16x32_bf16 v[36:39], v[132:135], v[212:215], v[36:39]
	v_mfma_f32_16x16x32_bf16 v[32:35], v[140:143], v[212:215], v[32:35]
	s_setprio 0
	s_setprio 1
	v_mfma_f32_16x16x32_bf16 v[28:31], v[144:147], v[160:163], v[28:31]
	v_mfma_f32_16x16x32_bf16 v[24:27], v[152:155], v[160:163], v[24:27]
	v_mfma_f32_16x16x32_bf16 v[20:23], v[144:147], v[168:171], v[20:23]
	v_mfma_f32_16x16x32_bf16 v[16:19], v[152:155], v[168:171], v[16:19]
	v_mfma_f32_16x16x32_bf16 v[12:15], v[144:147], v[200:203], v[12:15]
	v_mfma_f32_16x16x32_bf16 v[8:11], v[152:155], v[200:203], v[8:11]
	v_mfma_f32_16x16x32_bf16 v[4:7], v[144:147], v[208:211], v[4:7]
	v_mfma_f32_16x16x32_bf16 v[0:3], v[152:155], v[208:211], v[0:3]
	v_mfma_f32_16x16x32_bf16 v[28:31], v[148:151], v[164:167], v[28:31]
	v_mfma_f32_16x16x32_bf16 v[24:27], v[156:159], v[164:167], v[24:27]
	v_mfma_f32_16x16x32_bf16 v[20:23], v[148:151], v[172:175], v[20:23]
	v_mfma_f32_16x16x32_bf16 v[16:19], v[156:159], v[172:175], v[16:19]
	v_mfma_f32_16x16x32_bf16 v[12:15], v[148:151], v[204:207], v[12:15]
	v_mfma_f32_16x16x32_bf16 v[8:11], v[156:159], v[204:207], v[8:11]
	v_mfma_f32_16x16x32_bf16 v[4:7], v[148:151], v[212:215], v[4:7]
	v_mfma_f32_16x16x32_bf16 v[0:3], v[156:159], v[212:215], v[0:3]
	s_setprio 0
	s_barrier
	s_add_i32 s81, 0, 0x18000
	s_add_i32 s82, 0, 0x1c000
	v_add_u32_e32 v140, s81, v197
	v_add_u32_e32 v156, s82, v197
	ds_read_b128 v[128:131], v140
	ds_read_b128 v[132:135], v140 offset:1024
	ds_read_b128 v[136:139], v140 offset:2048
	ds_read_b128 v[140:143], v140 offset:3072
	ds_read_b128 v[144:147], v156
	ds_read_b128 v[148:151], v156 offset:1024
	ds_read_b128 v[152:155], v156 offset:2048
	ds_read_b128 v[156:159], v156 offset:3072
	s_add_u32 s36, s36, 0x80000
	s_addc_u32 s37, s37, 0
	s_mov_b32 m0, s42
	ds_read_b128 v[160:163], v199 offset:32768
	ds_read_b128 v[164:167], v199 offset:33792
	ds_read_b128 v[168:171], v199 offset:34816
	ds_read_b128 v[172:175], v199 offset:35840
	ds_read_b128 v[200:203], v199 offset:36864
	ds_read_b128 v[204:207], v199 offset:37888
	ds_read_b128 v[208:211], v199 offset:38912
	ds_read_b128 v[212:215], v199 offset:39936
	global_load_lds_dwordx4 v182, s[36:37]
	s_mov_b32 m0, s43
	s_nop 0
	global_load_lds_dwordx4 v178, s[36:37]
	s_waitcnt vmcnt(8)
	s_waitcnt lgkmcnt(0)
	s_barrier
	s_setprio 1
	s_waitcnt lgkmcnt(0)
	v_mfma_f32_16x16x32_bf16 v[124:127], v[128:131], v[160:163], v[124:127]
	v_mfma_f32_16x16x32_bf16 v[120:123], v[136:139], v[160:163], v[120:123]
	v_mfma_f32_16x16x32_bf16 v[116:119], v[128:131], v[168:171], v[116:119]
	v_mfma_f32_16x16x32_bf16 v[112:115], v[136:139], v[168:171], v[112:115]
	v_mfma_f32_16x16x32_bf16 v[108:111], v[128:131], v[200:203], v[108:111]
	v_mfma_f32_16x16x32_bf16 v[104:107], v[136:139], v[200:203], v[104:107]
	v_mfma_f32_16x16x32_bf16 v[100:103], v[128:131], v[208:211], v[100:103]
	v_mfma_f32_16x16x32_bf16 v[96:99], v[136:139], v[208:211], v[96:99]
	v_mfma_f32_16x16x32_bf16 v[124:127], v[132:135], v[164:167], v[124:127]
	v_mfma_f32_16x16x32_bf16 v[120:123], v[140:143], v[164:167], v[120:123]
	v_mfma_f32_16x16x32_bf16 v[116:119], v[132:135], v[172:175], v[116:119]
	v_mfma_f32_16x16x32_bf16 v[112:115], v[140:143], v[172:175], v[112:115]
	v_mfma_f32_16x16x32_bf16 v[108:111], v[132:135], v[204:207], v[108:111]
	v_mfma_f32_16x16x32_bf16 v[104:107], v[140:143], v[204:207], v[104:107]
	v_mfma_f32_16x16x32_bf16 v[100:103], v[132:135], v[212:215], v[100:103]
	v_mfma_f32_16x16x32_bf16 v[96:99], v[140:143], v[212:215], v[96:99]
	s_setprio 0
	s_setprio 1
	v_mfma_f32_16x16x32_bf16 v[92:95], v[144:147], v[160:163], v[92:95]
	v_mfma_f32_16x16x32_bf16 v[88:91], v[152:155], v[160:163], v[88:91]
	v_mfma_f32_16x16x32_bf16 v[84:87], v[144:147], v[168:171], v[84:87]
	v_mfma_f32_16x16x32_bf16 v[80:83], v[152:155], v[168:171], v[80:83]
	v_mfma_f32_16x16x32_bf16 v[76:79], v[144:147], v[200:203], v[76:79]
	v_mfma_f32_16x16x32_bf16 v[72:75], v[152:155], v[200:203], v[72:75]
	v_mfma_f32_16x16x32_bf16 v[68:71], v[144:147], v[208:211], v[68:71]
	v_mfma_f32_16x16x32_bf16 v[64:67], v[152:155], v[208:211], v[64:67]
	v_mfma_f32_16x16x32_bf16 v[92:95], v[148:151], v[164:167], v[92:95]
	v_mfma_f32_16x16x32_bf16 v[88:91], v[156:159], v[164:167], v[88:91]
	v_mfma_f32_16x16x32_bf16 v[84:87], v[148:151], v[172:175], v[84:87]
	v_mfma_f32_16x16x32_bf16 v[80:83], v[156:159], v[172:175], v[80:83]
	v_mfma_f32_16x16x32_bf16 v[76:79], v[148:151], v[204:207], v[76:79]
	v_mfma_f32_16x16x32_bf16 v[72:75], v[156:159], v[204:207], v[72:75]
	v_mfma_f32_16x16x32_bf16 v[68:71], v[148:151], v[212:215], v[68:71]
	v_mfma_f32_16x16x32_bf16 v[64:67], v[156:159], v[212:215], v[64:67]
	s_setprio 0
	s_barrier
; #define PG8_STAGE(bufoff, gbase, voff) do { _Pragma("unroll") for (int _i = 0; _i < 2; ++_i) \
;         __builtin_amdgcn_global_load_lds((const unsigned*)((const char*)(gbase) + (voff)[_i]), (LAS unsigned*)(lds + (bufoff) + ldsw + _i * 8192), 16, 0, 0); } while (0)
; #define PG8_LDA(dst, b, h) do { _Pragma("unroll") for (int m = 0; m < 4; ++m) _Pragma("unroll") for (int k = 0; k < 2; ++k) dst[m][k] = *(const LAS bf16x8*)(lds + PG8_SA(b, h) + aoff + m * 2048 + k * 1024); } while (0)
; #define PG8_WAIT_V(n) asm volatile("s_waitcnt vmcnt(" #n ")" ::: "memory")
; #define PG8_WAIT_L(n) asm volatile("s_waitcnt lgkmcnt(" #n ")" ::: "memory")
; #define PG8_BAR __builtin_amdgcn_s_barrier()
; #define PG8_SCHED __builtin_amdgcn_sched_barrier(0)
; template <class Epi, class Sched, bool F8 = false>
; __device__ __forceinline__ void gemm_phase(LAS unsigned char* lds, const Gemm g, const Sched& S, const Epi& E) {
;     ...
;             PG8_LDA(At, 1, 1); PG8_STAGE(PG8_SB(1, 0), b3, voffB); PG8_STAGE(PG8_SB(1, 1), b3 + hstepB, voffB); PG8_STAGE(PG8_SA(1, 0), a3, voffA);
;             PG8_WAIT_V(8); PG8_WAIT_L(0); PG8_BAR; PG8_MMA(1, 0, At, B0); PG8_MMA(1, 1, At, B1); PG8_BAR; PG8_SCHED;
;         }
;         if (wr == 0) PG8_BAR;
	s_add_i32 s36, s81, s38
	s_add_i32 m0, s36, 0xffffff80
	ds_read_b128 v[160:163], v199 offset:49152
	ds_read_b128 v[164:167], v199 offset:50176
	ds_read_b128 v[168:171], v199 offset:51200
	ds_read_b128 v[172:175], v199 offset:52224
	ds_read_b128 v[200:203], v199 offset:53248
	ds_read_b128 v[204:207], v199 offset:54272
	ds_read_b128 v[208:211], v199 offset:55296
	ds_read_b128 v[212:215], v199 offset:56320
	global_load_lds_dwordx4 v[216:217], off offset:128
	s_add_i32 m0, s36, 0x1f80
	s_add_u32 s34, s34, 0x80080
	s_addc_u32 s35, s35, 0
	s_add_i32 s36, s82, s38
	global_load_lds_dwordx4 v[218:219], off offset:128
	s_mov_b32 m0, s36
	s_nop 0
	global_load_lds_dwordx4 v180, s[34:35]
	s_add_i32 m0, s36, 0x2000
	s_nop 0
	global_load_lds_dwordx4 v176, s[34:35]
	s_add_i32 m0, s45, 0xffffff80
	s_nop 0
	global_load_lds_dwordx4 v[220:221], off offset:128
	s_add_i32 m0, s47, 0xffffff80
	s_nop 0
	global_load_lds_dwordx4 v[222:223], off offset:128
	s_waitcnt vmcnt(8)
	s_waitcnt lgkmcnt(0)
	s_barrier
	s_setprio 1
	s_waitcnt lgkmcnt(0)
	v_mfma_f32_16x16x32_bf16 v[60:63], v[128:131], v[160:163], v[60:63]
	v_mfma_f32_16x16x32_bf16 v[56:59], v[136:139], v[160:163], v[56:59]
	v_mfma_f32_16x16x32_bf16 v[52:55], v[128:131], v[168:171], v[52:55]
	v_mfma_f32_16x16x32_bf16 v[48:51], v[136:139], v[168:171], v[48:51]
	v_mfma_f32_16x16x32_bf16 v[44:47], v[128:131], v[200:203], v[44:47]
	v_mfma_f32_16x16x32_bf16 v[40:43], v[136:139], v[200:203], v[40:43]
	v_mfma_f32_16x16x32_bf16 v[36:39], v[128:131], v[208:211], v[36:39]
	v_mfma_f32_16x16x32_bf16 v[32:35], v[136:139], v[208:211], v[32:35]
	v_mfma_f32_16x16x32_bf16 v[60:63], v[132:135], v[164:167], v[60:63]
	v_mfma_f32_16x16x32_bf16 v[56:59], v[140:143], v[164:167], v[56:59]
	v_mfma_f32_16x16x32_bf16 v[52:55], v[132:135], v[172:175], v[52:55]
	v_mfma_f32_16x16x32_bf16 v[48:51], v[140:143], v[172:175], v[48:51]
	v_mfma_f32_16x16x32_bf16 v[44:47], v[132:135], v[204:207], v[44:47]
	v_mfma_f32_16x16x32_bf16 v[40:43], v[140:143], v[204:207], v[40:43]
	v_mfma_f32_16x16x32_bf16 v[36:39], v[132:135], v[212:215], v[36:39]
	v_mfma_f32_16x16x32_bf16 v[32:35], v[140:143], v[212:215], v[32:35]
	s_setprio 0
	s_setprio 1
	v_mfma_f32_16x16x32_bf16 v[28:31], v[144:147], v[160:163], v[28:31]
	v_mfma_f32_16x16x32_bf16 v[24:27], v[152:155], v[160:163], v[24:27]
	v_mfma_f32_16x16x32_bf16 v[20:23], v[144:147], v[168:171], v[20:23]
	v_mfma_f32_16x16x32_bf16 v[16:19], v[152:155], v[168:171], v[16:19]
	v_mfma_f32_16x16x32_bf16 v[12:15], v[144:147], v[200:203], v[12:15]
	v_mfma_f32_16x16x32_bf16 v[8:11], v[152:155], v[200:203], v[8:11]
	v_mfma_f32_16x16x32_bf16 v[4:7], v[144:147], v[208:211], v[4:7]
	v_mfma_f32_16x16x32_bf16 v[0:3], v[152:155], v[208:211], v[0:3]
	v_mfma_f32_16x16x32_bf16 v[28:31], v[148:151], v[164:167], v[28:31]
	v_mfma_f32_16x16x32_bf16 v[24:27], v[156:159], v[164:167], v[24:27]
	v_mfma_f32_16x16x32_bf16 v[20:23], v[148:151], v[172:175], v[20:23]
	v_mfma_f32_16x16x32_bf16 v[16:19], v[156:159], v[172:175], v[16:19]
	v_mfma_f32_16x16x32_bf16 v[12:15], v[148:151], v[204:207], v[12:15]
	v_mfma_f32_16x16x32_bf16 v[8:11], v[156:159], v[204:207], v[8:11]
	v_mfma_f32_16x16x32_bf16 v[4:7], v[148:151], v[212:215], v[4:7]
	v_mfma_f32_16x16x32_bf16 v[0:3], v[156:159], v[212:215], v[0:3]
	s_setprio 0
	s_barrier
	s_add_u32 s30, s30, 0x100
	s_addc_u32 s31, s31, 0
	s_add_u32 s78, s78, 0x100
	s_addc_u32 s79, s79, 0
	s_cmp_ge_i32 s80, s9
	s_mov_b32 s34, s80
	s_cbranch_scc0 .LBB0_753
	s_and_b64 vcc, exec, s[18:19]
	s_cbranch_vccz .LBB0_756
	s_barrier

; #define PG8_STAGE(bufoff, gbase, voff) do { _Pragma("unroll") for (int _i = 0; _i < 2; ++_i) \
;         __builtin_amdgcn_global_load_lds((const unsigned*)((const char*)(gbase) + (voff)[_i]), (LAS unsigned*)(lds + (bufoff) + ldsw + _i * 8192), 16, 0, 0); } while (0)
; #define PG8_LDA(dst, b, h) do { _Pragma("unroll") for (int m = 0; m < 4; ++m) _Pragma("unroll") for (int k = 0; k < 2; ++k) dst[m][k] = *(const LAS bf16x8*)(lds + PG8_SA(b, h) + aoff + m * 2048 + k * 1024); } while (0)
; #define PG8_LDB(dst, b, h) do { _Pragma("unroll") for (int n = 0; n < 2; ++n) _Pragma("unroll") for (int k = 0; k < 2; ++k) dst[n][k] = *(const LAS bf16x8*)(lds + PG8_SB(b, h) + boff + n * 2048 + k * 1024); } while (0)
; #define PG8_WAIT_V(n) asm volatile("s_waitcnt vmcnt(" #n ")" ::: "memory")
; #define PG8_WAIT_L(n) asm volatile("s_waitcnt lgkmcnt(" #n ")" ::: "memory")
; #define PG8_BAR __builtin_amdgcn_s_barrier()
; #define PG8_SCHED __builtin_amdgcn_sched_barrier(0)
; template <class Epi, class Sched, bool F8 = false>
; __device__ __forceinline__ void gemm_phase(LAS unsigned char* lds, const Gemm g, const Sched& S, const Epi& E) {
;     ...
;         for (int t = 0; t < nt; t += 2) {
;             const bool last = (t == nt - 2);
;             const char* a1 = cA + (size_t)(t + 1) * kstep;
;             const char* a2 = last ? nA : cA + (size_t)(t + 2) * kstep; const char* b2 = last ? nB : cB + (size_t)(t + 2) * kstep;
;             const char* a3 = a2 + kstep; const char* b3 = b2 + kstep;
;             PG8_LDB(B0, 0, 0); PG8_LDB(B1, 0, 1); PG8_SCHED; PG8_LDA(At, 0, 0); PG8_STAGE(PG8_SA(1, 1), a1 + hstepA, voffA);
;             PG8_WAIT_V(8); PG8_WAIT_L(0); PG8_BAR; PG8_MMA(0, 0, At, B0); PG8_MMA(0, 1, At, B1); PG8_BAR; PG8_SCHED;
;             PG8_LDA(At, 0, 1); PG8_STAGE(PG8_SB(0, 0), b2, voffB); PG8_STAGE(PG8_SB(0, 1), b2 + hstepB, voffB); PG8_STAGE(PG8_SA(0, 0), a2, voffA);
.LBB0_825:
	ds_read_b128 v[168:171], v164
	ds_read_b128 v[172:175], v164 offset:1024
	ds_read_b128 v[176:179], v164 offset:2048
	ds_read_b128 v[180:183], v164 offset:3072
	ds_read_b128 v[184:187], v165
	ds_read_b128 v[192:195], v165 offset:1024
	ds_read_b128 v[196:199], v165 offset:2048
	ds_read_b128 v[200:203], v165 offset:3072
	s_add_u32 s38, s36, 0xfff80080
	s_addc_u32 s39, s37, -1
	s_cmp_eq_u32 s58, 28
	s_cselect_b32 s41, s10, s39
	s_cselect_b32 s40, s27, s38
	s_cselect_b32 s39, s25, s57
	s_cselect_b32 s38, s35, s56
	s_add_i32 m0, s43, 0xc000
	ds_read_b128 v[204:207], v166
	ds_read_b128 v[208:211], v166 offset:1024
	ds_read_b128 v[212:215], v166 offset:2048
	ds_read_b128 v[216:219], v166 offset:3072
	ds_read_b128 v[220:223], v166 offset:4096
	ds_read_b128 v[224:227], v166 offset:5120
	ds_read_b128 v[228:231], v166 offset:6144
	ds_read_b128 v[232:235], v166 offset:7168
	global_load_lds_dwordx4 v152, s[36:37]
	s_add_i32 m0, s43, 0xe000
	s_nop 0
	global_load_lds_dwordx4 v154, s[36:37]
	s_waitcnt vmcnt(8)
	s_waitcnt lgkmcnt(0)
	s_barrier
	s_setprio 1
	s_waitcnt lgkmcnt(0)
	v_mfma_f32_16x16x32_bf16 v[124:127], v[168:171], v[204:207], v[124:127]
	v_mfma_f32_16x16x32_bf16 v[120:123], v[176:179], v[204:207], v[120:123]
	v_mfma_f32_16x16x32_bf16 v[116:119], v[168:171], v[212:215], v[116:119]
	v_mfma_f32_16x16x32_bf16 v[108:111], v[176:179], v[212:215], v[108:111]
	v_mfma_f32_16x16x32_bf16 v[100:103], v[168:171], v[220:223], v[100:103]
	v_mfma_f32_16x16x32_bf16 v[92:95], v[176:179], v[220:223], v[92:95]
	v_mfma_f32_16x16x32_bf16 v[84:87], v[168:171], v[228:231], v[84:87]
	v_mfma_f32_16x16x32_bf16 v[76:79], v[176:179], v[228:231], v[76:79]
	v_mfma_f32_16x16x32_bf16 v[124:127], v[172:175], v[208:211], v[124:127]
	v_mfma_f32_16x16x32_bf16 v[120:123], v[180:183], v[208:211], v[120:123]
	v_mfma_f32_16x16x32_bf16 v[116:119], v[172:175], v[216:219], v[116:119]
	v_mfma_f32_16x16x32_bf16 v[108:111], v[180:183], v[216:219], v[108:111]
	v_mfma_f32_16x16x32_bf16 v[100:103], v[172:175], v[224:227], v[100:103]
	v_mfma_f32_16x16x32_bf16 v[92:95], v[180:183], v[224:227], v[92:95]
	v_mfma_f32_16x16x32_bf16 v[84:87], v[172:175], v[232:235], v[84:87]
	v_mfma_f32_16x16x32_bf16 v[76:79], v[180:183], v[232:235], v[76:79]
	s_setprio 0
	s_setprio 1
	v_mfma_f32_16x16x32_bf16 v[112:115], v[184:187], v[204:207], v[112:115]
	v_mfma_f32_16x16x32_bf16 v[104:107], v[196:199], v[204:207], v[104:107]
	v_mfma_f32_16x16x32_bf16 v[96:99], v[184:187], v[212:215], v[96:99]
	v_mfma_f32_16x16x32_bf16 v[88:91], v[196:199], v[212:215], v[88:91]
	v_mfma_f32_16x16x32_bf16 v[80:83], v[184:187], v[220:223], v[80:83]
	v_mfma_f32_16x16x32_bf16 v[72:75], v[196:199], v[220:223], v[72:75]
	v_mfma_f32_16x16x32_bf16 v[68:71], v[184:187], v[228:231], v[68:71]
	v_mfma_f32_16x16x32_bf16 v[64:67], v[196:199], v[228:231], v[64:67]
	v_mfma_f32_16x16x32_bf16 v[112:115], v[192:195], v[208:211], v[112:115]
	v_mfma_f32_16x16x32_bf16 v[104:107], v[200:203], v[208:211], v[104:107]
	v_mfma_f32_16x16x32_bf16 v[96:99], v[192:195], v[216:219], v[96:99]
	v_mfma_f32_16x16x32_bf16 v[88:91], v[200:203], v[216:219], v[88:91]
	v_mfma_f32_16x16x32_bf16 v[80:83], v[192:195], v[224:227], v[80:83]
	v_mfma_f32_16x16x32_bf16 v[72:75], v[200:203], v[224:227], v[72:75]
	v_mfma_f32_16x16x32_bf16 v[68:71], v[192:195], v[232:235], v[68:71]
	v_mfma_f32_16x16x32_bf16 v[64:67], v[200:203], v[232:235], v[64:67]
	s_setprio 0
	s_barrier
	s_add_i32 s59, s50, s23
	v_lshl_add_u64 v[160:161], s[38:39], 0, v[132:133]
	s_mov_b32 m0, s59
	ds_read_b128 v[204:207], v166 offset:16384
	ds_read_b128 v[208:211], v166 offset:17408
	ds_read_b128 v[212:215], v166 offset:18432
	ds_read_b128 v[216:219], v166 offset:19456
	ds_read_b128 v[220:223], v166 offset:20480
	ds_read_b128 v[224:227], v166 offset:21504
	ds_read_b128 v[228:231], v166 offset:22528
	ds_read_b128 v[232:235], v166 offset:23552
	global_load_lds_dwordx4 v[160:161], off
	s_add_i32 m0, s59, 0x2000
	s_add_u32 s72, s38, 0x80000
	v_lshl_add_u64 v[188:189], s[38:39], 0, v[128:129]
	s_addc_u32 s73, s39, 0
	s_add_i32 s59, s91, s23
	global_load_lds_dwordx4 v[188:189], off
	s_mov_b32 m0, s59
	v_lshl_add_u64 v[238:239], s[40:41], 0, v[130:131]
	global_load_lds_dwordx4 v132, s[72:73]
	s_add_i32 m0, s59, 0x2000
	s_nop 0
	global_load_lds_dwordx4 v128, s[72:73]
	v_lshl_add_u64 v[236:237], s[40:41], 0, v[134:135]
	s_mov_b32 m0, s43
	s_nop 0
	global_load_lds_dwordx4 v[236:237], off
	s_mov_b32 m0, s44
	s_nop 0
	global_load_lds_dwordx4 v[238:239], off
	s_waitcnt vmcnt(8)
	s_waitcnt lgkmcnt(0)
	s_barrier
; #define PG8_STAGE(bufoff, gbase, voff) do { _Pragma("unroll") for (int _i = 0; _i < 2; ++_i) \
;         __builtin_amdgcn_global_load_lds((const unsigned*)((const char*)(gbase) + (voff)[_i]), (LAS unsigned*)(lds + (bufoff) + ldsw + _i * 8192), 16, 0, 0); } while (0)
; #define PG8_LDA(dst, b, h) do { _Pragma("unroll") for (int m = 0; m < 4; ++m) _Pragma("unroll") for (int k = 0; k < 2; ++k) dst[m][k] = *(const LAS bf16x8*)(lds + PG8_SA(b, h) + aoff + m * 2048 + k * 1024); } while (0)
; #define PG8_LDB(dst, b, h) do { _Pragma("unroll") for (int n = 0; n < 2; ++n) _Pragma("unroll") for (int k = 0; k < 2; ++k) dst[n][k] = *(const LAS bf16x8*)(lds + PG8_SB(b, h) + boff + n * 2048 + k * 1024); } while (0)
; #define PG8_WAIT_V(n) asm volatile("s_waitcnt vmcnt(" #n ")" ::: "memory")
; #define PG8_WAIT_L(n) asm volatile("s_waitcnt lgkmcnt(" #n ")" ::: "memory")
; #define PG8_BAR __builtin_amdgcn_s_barrier()
; #define PG8_SCHED __builtin_amdgcn_sched_barrier(0)
; template <class Epi, class Sched, bool F8 = false>
; __device__ __forceinline__ void gemm_phase(LAS unsigned char* lds, const Gemm g, const Sched& S, const Epi& E) {
;     ...
;             PG8_WAIT_V(8); PG8_WAIT_L(0); PG8_BAR; PG8_MMA(1, 0, At, B0); PG8_MMA(1, 1, At, B1); PG8_BAR; PG8_SCHED;
;             PG8_LDB(B0, 1, 0); PG8_LDB(B1, 1, 1); PG8_SCHED; PG8_LDA(At, 1, 0); PG8_STAGE(PG8_SA(0, 1), a2 + hstepA, voffA);
;             PG8_WAIT_V(8); PG8_WAIT_L(0); PG8_BAR; PG8_MMA(0, 0, At, B0); PG8_MMA(0, 1, At, B1); PG8_BAR; PG8_SCHED;
	s_setprio 1
	s_waitcnt lgkmcnt(0)
	v_mfma_f32_16x16x32_bf16 v[60:63], v[168:171], v[204:207], v[60:63]
	v_mfma_f32_16x16x32_bf16 v[56:59], v[176:179], v[204:207], v[56:59]
	v_mfma_f32_16x16x32_bf16 v[52:55], v[168:171], v[212:215], v[52:55]
	v_mfma_f32_16x16x32_bf16 v[44:47], v[176:179], v[212:215], v[44:47]
	v_mfma_f32_16x16x32_bf16 v[36:39], v[168:171], v[220:223], v[36:39]
	v_mfma_f32_16x16x32_bf16 v[28:31], v[176:179], v[220:223], v[28:31]
	v_mfma_f32_16x16x32_bf16 v[20:23], v[168:171], v[228:231], v[20:23]
	v_mfma_f32_16x16x32_bf16 v[12:15], v[176:179], v[228:231], v[12:15]
	v_mfma_f32_16x16x32_bf16 v[60:63], v[172:175], v[208:211], v[60:63]
	v_mfma_f32_16x16x32_bf16 v[56:59], v[180:183], v[208:211], v[56:59]
	v_mfma_f32_16x16x32_bf16 v[52:55], v[172:175], v[216:219], v[52:55]
	v_mfma_f32_16x16x32_bf16 v[44:47], v[180:183], v[216:219], v[44:47]
	v_mfma_f32_16x16x32_bf16 v[36:39], v[172:175], v[224:227], v[36:39]
	v_mfma_f32_16x16x32_bf16 v[28:31], v[180:183], v[224:227], v[28:31]
	v_mfma_f32_16x16x32_bf16 v[20:23], v[172:175], v[232:235], v[20:23]
	v_mfma_f32_16x16x32_bf16 v[12:15], v[180:183], v[232:235], v[12:15]
	s_setprio 0
	s_setprio 1
	v_mfma_f32_16x16x32_bf16 v[48:51], v[184:187], v[204:207], v[48:51]
	v_mfma_f32_16x16x32_bf16 v[40:43], v[196:199], v[204:207], v[40:43]
	v_mfma_f32_16x16x32_bf16 v[32:35], v[184:187], v[212:215], v[32:35]
	v_mfma_f32_16x16x32_bf16 v[24:27], v[196:199], v[212:215], v[24:27]
	v_mfma_f32_16x16x32_bf16 v[16:19], v[184:187], v[220:223], v[16:19]
	v_mfma_f32_16x16x32_bf16 v[8:11], v[196:199], v[220:223], v[8:11]
	v_mfma_f32_16x16x32_bf16 v[4:7], v[184:187], v[228:231], v[4:7]
	v_mfma_f32_16x16x32_bf16 v[0:3], v[196:199], v[228:231], v[0:3]
	v_mfma_f32_16x16x32_bf16 v[48:51], v[192:195], v[208:211], v[48:51]
	v_mfma_f32_16x16x32_bf16 v[40:43], v[200:203], v[208:211], v[40:43]
	v_mfma_f32_16x16x32_bf16 v[32:35], v[192:195], v[216:219], v[32:35]
	v_mfma_f32_16x16x32_bf16 v[24:27], v[200:203], v[216:219], v[24:27]
	v_mfma_f32_16x16x32_bf16 v[16:19], v[192:195], v[224:227], v[16:19]
	v_mfma_f32_16x16x32_bf16 v[8:11], v[200:203], v[224:227], v[8:11]
	v_mfma_f32_16x16x32_bf16 v[4:7], v[192:195], v[232:235], v[4:7]
	v_mfma_f32_16x16x32_bf16 v[0:3], v[200:203], v[232:235], v[0:3]
	s_setprio 0
	s_barrier
	s_add_i32 s59, 0, 0x18000
	v_add_u32_e32 v167, s59, v162
	s_add_i32 s72, 0, 0x1c000
	ds_read_b128 v[168:171], v167
	ds_read_b128 v[172:175], v167 offset:1024
	ds_read_b128 v[176:179], v167 offset:2048
	ds_read_b128 v[180:183], v167 offset:3072
	v_add_u32_e32 v167, s72, v162
	ds_read_b128 v[184:187], v167
	ds_read_b128 v[192:195], v167 offset:1024
	ds_read_b128 v[196:199], v167 offset:2048
	ds_read_b128 v[200:203], v167 offset:3072
	s_add_u32 s40, s40, 0x80000
	s_addc_u32 s41, s41, 0
	s_mov_b32 m0, s45
	ds_read_b128 v[204:207], v166 offset:32768
	ds_read_b128 v[208:211], v166 offset:33792
	ds_read_b128 v[212:215], v166 offset:34816
	ds_read_b128 v[216:219], v166 offset:35840
	ds_read_b128 v[220:223], v166 offset:36864
	ds_read_b128 v[224:227], v166 offset:37888
	ds_read_b128 v[228:231], v166 offset:38912
	ds_read_b128 v[232:235], v166 offset:39936
	global_load_lds_dwordx4 v134, s[40:41]
	s_mov_b32 m0, s47
	s_nop 0
	global_load_lds_dwordx4 v130, s[40:41]
	s_waitcnt vmcnt(8)
	s_waitcnt lgkmcnt(0)
	s_barrier
	s_setprio 1
	s_waitcnt lgkmcnt(0)
	v_mfma_f32_16x16x32_bf16 v[124:127], v[168:171], v[204:207], v[124:127]
	v_mfma_f32_16x16x32_bf16 v[120:123], v[176:179], v[204:207], v[120:123]
	v_mfma_f32_16x16x32_bf16 v[116:119], v[168:171], v[212:215], v[116:119]
	v_mfma_f32_16x16x32_bf16 v[108:111], v[176:179], v[212:215], v[108:111]
	v_mfma_f32_16x16x32_bf16 v[100:103], v[168:171], v[220:223], v[100:103]
	v_mfma_f32_16x16x32_bf16 v[92:95], v[176:179], v[220:223], v[92:95]
	v_mfma_f32_16x16x32_bf16 v[84:87], v[168:171], v[228:231], v[84:87]
	v_mfma_f32_16x16x32_bf16 v[76:79], v[176:179], v[228:231], v[76:79]
	v_mfma_f32_16x16x32_bf16 v[124:127], v[172:175], v[208:211], v[124:127]
	v_mfma_f32_16x16x32_bf16 v[120:123], v[180:183], v[208:211], v[120:123]
	v_mfma_f32_16x16x32_bf16 v[116:119], v[172:175], v[216:219], v[116:119]
	v_mfma_f32_16x16x32_bf16 v[108:111], v[180:183], v[216:219], v[108:111]
	v_mfma_f32_16x16x32_bf16 v[100:103], v[172:175], v[224:227], v[100:103]
	v_mfma_f32_16x16x32_bf16 v[92:95], v[180:183], v[224:227], v[92:95]
	v_mfma_f32_16x16x32_bf16 v[84:87], v[172:175], v[232:235], v[84:87]
	v_mfma_f32_16x16x32_bf16 v[76:79], v[180:183], v[232:235], v[76:79]
	s_setprio 0
	s_setprio 1
	v_mfma_f32_16x16x32_bf16 v[112:115], v[184:187], v[204:207], v[112:115]
	v_mfma_f32_16x16x32_bf16 v[104:107], v[196:199], v[204:207], v[104:107]
	v_mfma_f32_16x16x32_bf16 v[96:99], v[184:187], v[212:215], v[96:99]
	v_mfma_f32_16x16x32_bf16 v[88:91], v[196:199], v[212:215], v[88:91]
	v_mfma_f32_16x16x32_bf16 v[80:83], v[184:187], v[220:223], v[80:83]
	v_mfma_f32_16x16x32_bf16 v[72:75], v[196:199], v[220:223], v[72:75]
	v_mfma_f32_16x16x32_bf16 v[68:71], v[184:187], v[228:231], v[68:71]
	v_mfma_f32_16x16x32_bf16 v[64:67], v[196:199], v[228:231], v[64:67]
	v_mfma_f32_16x16x32_bf16 v[112:115], v[192:195], v[208:211], v[112:115]
	v_mfma_f32_16x16x32_bf16 v[104:107], v[200:203], v[208:211], v[104:107]
	v_mfma_f32_16x16x32_bf16 v[96:99], v[192:195], v[216:219], v[96:99]
	v_mfma_f32_16x16x32_bf16 v[88:91], v[200:203], v[216:219], v[88:91]
	v_mfma_f32_16x16x32_bf16 v[80:83], v[192:195], v[224:227], v[80:83]
	v_mfma_f32_16x16x32_bf16 v[72:75], v[200:203], v[224:227], v[72:75]
	v_mfma_f32_16x16x32_bf16 v[68:71], v[192:195], v[232:235], v[68:71]
	v_mfma_f32_16x16x32_bf16 v[64:67], v[200:203], v[232:235], v[64:67]
	s_setprio 0
	s_barrier
; #define PG8_STAGE(bufoff, gbase, voff) do { _Pragma("unroll") for (int _i = 0; _i < 2; ++_i) \
;         __builtin_amdgcn_global_load_lds((const unsigned*)((const char*)(gbase) + (voff)[_i]), (LAS unsigned*)(lds + (bufoff) + ldsw + _i * 8192), 16, 0, 0); } while (0)
; #define PG8_LDA(dst, b, h) do { _Pragma("unroll") for (int m = 0; m < 4; ++m) _Pragma("unroll") for (int k = 0; k < 2; ++k) dst[m][k] = *(const LAS bf16x8*)(lds + PG8_SA(b, h) + aoff + m * 2048 + k * 1024); } while (0)
; #define PG8_WAIT_V(n) asm volatile("s_waitcnt vmcnt(" #n ")" ::: "memory")
; #define PG8_WAIT_L(n) asm volatile("s_waitcnt lgkmcnt(" #n ")" ::: "memory")
; #define PG8_BAR __builtin_amdgcn_s_barrier()
; #define PG8_SCHED __builtin_amdgcn_sched_barrier(0)
; template <class Epi, class Sched, bool F8 = false>
; __device__ __forceinline__ void gemm_phase(LAS unsigned char* lds, const Gemm g, const Sched& S, const Epi& E) {
;     ...
;             PG8_LDA(At, 1, 1); PG8_STAGE(PG8_SB(1, 0), b3, voffB); PG8_STAGE(PG8_SB(1, 1), b3 + hstepB, voffB); PG8_STAGE(PG8_SA(1, 0), a3, voffA);
;             PG8_WAIT_V(8); PG8_WAIT_L(0); PG8_BAR; PG8_MMA(1, 0, At, B0); PG8_MMA(1, 1, At, B1); PG8_BAR; PG8_SCHED;
;         }
;         if (wr == 0) PG8_BAR;
	s_add_i32 s40, s59, s23
	s_add_i32 m0, s40, 0xffffff80
	ds_read_b128 v[204:207], v166 offset:49152
	ds_read_b128 v[208:211], v166 offset:50176
	ds_read_b128 v[212:215], v166 offset:51200
	ds_read_b128 v[216:219], v166 offset:52224
	ds_read_b128 v[220:223], v166 offset:53248
	ds_read_b128 v[224:227], v166 offset:54272
	ds_read_b128 v[228:231], v166 offset:55296
	ds_read_b128 v[232:235], v166 offset:56320
	global_load_lds_dwordx4 v[160:161], off offset:128
	s_add_i32 m0, s40, 0x1f80
	s_add_u32 s38, s38, 0x80080
	s_addc_u32 s39, s39, 0
	s_add_i32 s40, s72, s23
	global_load_lds_dwordx4 v[188:189], off offset:128
	s_mov_b32 m0, s40
	s_nop 0
	global_load_lds_dwordx4 v132, s[38:39]
	s_add_i32 m0, s40, 0x2000
	s_nop 0
	global_load_lds_dwordx4 v128, s[38:39]
	s_add_i32 m0, s48, 0xffffff80
	s_nop 0
	global_load_lds_dwordx4 v[236:237], off offset:128
	s_add_i32 m0, s49, 0xffffff80
	s_nop 0
	global_load_lds_dwordx4 v[238:239], off offset:128
	s_waitcnt vmcnt(8)
	s_waitcnt lgkmcnt(0)
	s_barrier
	s_setprio 1
	s_waitcnt lgkmcnt(0)
	v_mfma_f32_16x16x32_bf16 v[60:63], v[168:171], v[204:207], v[60:63]
	v_mfma_f32_16x16x32_bf16 v[56:59], v[176:179], v[204:207], v[56:59]
	v_mfma_f32_16x16x32_bf16 v[52:55], v[168:171], v[212:215], v[52:55]
	v_mfma_f32_16x16x32_bf16 v[44:47], v[176:179], v[212:215], v[44:47]
	v_mfma_f32_16x16x32_bf16 v[36:39], v[168:171], v[220:223], v[36:39]
	v_mfma_f32_16x16x32_bf16 v[28:31], v[176:179], v[220:223], v[28:31]
	v_mfma_f32_16x16x32_bf16 v[20:23], v[168:171], v[228:231], v[20:23]
	v_mfma_f32_16x16x32_bf16 v[12:15], v[176:179], v[228:231], v[12:15]
	v_mfma_f32_16x16x32_bf16 v[60:63], v[172:175], v[208:211], v[60:63]
	v_mfma_f32_16x16x32_bf16 v[56:59], v[180:183], v[208:211], v[56:59]
	v_mfma_f32_16x16x32_bf16 v[52:55], v[172:175], v[216:219], v[52:55]
	v_mfma_f32_16x16x32_bf16 v[44:47], v[180:183], v[216:219], v[44:47]
	v_mfma_f32_16x16x32_bf16 v[36:39], v[172:175], v[224:227], v[36:39]
	v_mfma_f32_16x16x32_bf16 v[28:31], v[180:183], v[224:227], v[28:31]
	v_mfma_f32_16x16x32_bf16 v[20:23], v[172:175], v[232:235], v[20:23]
	v_mfma_f32_16x16x32_bf16 v[12:15], v[180:183], v[232:235], v[12:15]
	s_setprio 0
	s_setprio 1
	v_mfma_f32_16x16x32_bf16 v[48:51], v[184:187], v[204:207], v[48:51]
	v_mfma_f32_16x16x32_bf16 v[40:43], v[196:199], v[204:207], v[40:43]
	v_mfma_f32_16x16x32_bf16 v[32:35], v[184:187], v[212:215], v[32:35]
	v_mfma_f32_16x16x32_bf16 v[24:27], v[196:199], v[212:215], v[24:27]
	v_mfma_f32_16x16x32_bf16 v[16:19], v[184:187], v[220:223], v[16:19]
	v_mfma_f32_16x16x32_bf16 v[8:11], v[196:199], v[220:223], v[8:11]
	v_mfma_f32_16x16x32_bf16 v[4:7], v[184:187], v[228:231], v[4:7]
	v_mfma_f32_16x16x32_bf16 v[0:3], v[196:199], v[228:231], v[0:3]
	v_mfma_f32_16x16x32_bf16 v[48:51], v[192:195], v[208:211], v[48:51]
	v_mfma_f32_16x16x32_bf16 v[40:43], v[200:203], v[208:211], v[40:43]
	v_mfma_f32_16x16x32_bf16 v[32:35], v[192:195], v[216:219], v[32:35]
	v_mfma_f32_16x16x32_bf16 v[24:27], v[200:203], v[216:219], v[24:27]
	v_mfma_f32_16x16x32_bf16 v[16:19], v[192:195], v[224:227], v[16:19]
	v_mfma_f32_16x16x32_bf16 v[8:11], v[200:203], v[224:227], v[8:11]
	v_mfma_f32_16x16x32_bf16 v[4:7], v[192:195], v[232:235], v[4:7]
	v_mfma_f32_16x16x32_bf16 v[0:3], v[200:203], v[232:235], v[0:3]
	s_setprio 0
	s_barrier
	s_add_i32 s58, s58, 2
	s_add_u32 s36, s36, 0x100
	s_addc_u32 s37, s37, 0
	s_add_u32 s56, s56, 0x100
	s_addc_u32 s57, s57, 0
	s_cmp_gt_u32 s58, 29
	s_cbranch_scc0 .LBB0_825
	s_and_b64 vcc, exec, s[20:21]
	s_cbranch_vccz .LBB0_828
	s_barrier

; #define PG8_STAGE(bufoff, gbase, voff) do { _Pragma("unroll") for (int _i = 0; _i < 2; ++_i) \
;         __builtin_amdgcn_global_load_lds((const unsigned*)((const char*)(gbase) + (voff)[_i]), (LAS unsigned*)(lds + (bufoff) + ldsw + _i * 8192), 16, 0, 0); } while (0)
; #define PG8_LDA(dst, b, h) do { _Pragma("unroll") for (int m = 0; m < 4; ++m) _Pragma("unroll") for (int k = 0; k < 2; ++k) dst[m][k] = *(const LAS bf16x8*)(lds + PG8_SA(b, h) + aoff + m * 2048 + k * 1024); } while (0)
; #define PG8_LDB(dst, b, h) do { _Pragma("unroll") for (int n = 0; n < 2; ++n) _Pragma("unroll") for (int k = 0; k < 2; ++k) dst[n][k] = *(const LAS bf16x8*)(lds + PG8_SB(b, h) + boff + n * 2048 + k * 1024); } while (0)
; #define PG8_WAIT_V(n) asm volatile("s_waitcnt vmcnt(" #n ")" ::: "memory")
; #define PG8_WAIT_L(n) asm volatile("s_waitcnt lgkmcnt(" #n ")" ::: "memory")
; #define PG8_BAR __builtin_amdgcn_s_barrier()
; #define PG8_SCHED __builtin_amdgcn_sched_barrier(0)
; template <class Epi, class Sched, bool F8 = false>
; __device__ __forceinline__ void gemm_phase(LAS unsigned char* lds, const Gemm g, const Sched& S, const Epi& E) {
;     ...
;         for (int t = 0; t < nt; t += 2) {
;             const bool last = (t == nt - 2);
;             const char* a1 = cA + (size_t)(t + 1) * kstep;
;             const char* a2 = last ? nA : cA + (size_t)(t + 2) * kstep; const char* b2 = last ? nB : cB + (size_t)(t + 2) * kstep;
;             const char* a3 = a2 + kstep; const char* b3 = b2 + kstep;
;             PG8_LDB(B0, 0, 0); PG8_LDB(B1, 0, 1); PG8_SCHED; PG8_LDA(At, 0, 0); PG8_STAGE(PG8_SA(1, 1), a1 + hstepA, voffA);
;             PG8_WAIT_V(8); PG8_WAIT_L(0); PG8_BAR; PG8_MMA(0, 0, At, B0); PG8_MMA(0, 1, At, B1); PG8_BAR; PG8_SCHED;
;             PG8_LDA(At, 0, 1); PG8_STAGE(PG8_SB(0, 0), b2, voffB); PG8_STAGE(PG8_SB(0, 1), b2 + hstepB, voffB); PG8_STAGE(PG8_SA(0, 0), a2, voffA);
.LBB0_954:
	ds_read_b128 v[150:153], v147
	ds_read_b128 v[154:157], v147 offset:1024
	ds_read_b128 v[158:161], v147 offset:2048
	ds_read_b128 v[162:165], v147 offset:3072
	ds_read_b128 v[166:169], v148
	ds_read_b128 v[170:173], v148 offset:1024
	ds_read_b128 v[174:177], v148 offset:2048
	ds_read_b128 v[178:181], v148 offset:3072
	s_add_u32 s30, s28, 0xfff80080
	s_addc_u32 s31, s29, -1
	s_cmp_eq_u32 s53, 28
	s_cselect_b32 s35, s21, s31
	s_cselect_b32 s34, s48, s30
	s_cselect_b32 s31, s19, s51
	s_cselect_b32 s30, s49, s50
	s_add_i32 m0, s27, 0xc000
	ds_read_b128 v[182:185], v149
	ds_read_b128 v[186:189], v149 offset:1024
	ds_read_b128 v[192:195], v149 offset:2048
	ds_read_b128 v[196:199], v149 offset:3072
	ds_read_b128 v[200:203], v149 offset:4096
	ds_read_b128 v[204:207], v149 offset:5120
	ds_read_b128 v[208:211], v149 offset:6144
	ds_read_b128 v[212:215], v149 offset:7168
	global_load_lds_dwordx4 v136, s[28:29]
	s_add_i32 m0, s27, 0xe000
	s_nop 0
	global_load_lds_dwordx4 v138, s[28:29]
	s_waitcnt vmcnt(8)
	s_waitcnt lgkmcnt(0)
	s_barrier
	s_setprio 1
	s_waitcnt lgkmcnt(0)
	v_mfma_f32_16x16x32_bf16 v[124:127], v[150:153], v[182:185], v[124:127]
	v_mfma_f32_16x16x32_bf16 v[120:123], v[158:161], v[182:185], v[120:123]
	v_mfma_f32_16x16x32_bf16 v[108:111], v[150:153], v[192:195], v[108:111]
	v_mfma_f32_16x16x32_bf16 v[104:107], v[158:161], v[192:195], v[104:107]
	v_mfma_f32_16x16x32_bf16 v[92:95], v[150:153], v[200:203], v[92:95]
	v_mfma_f32_16x16x32_bf16 v[88:91], v[158:161], v[200:203], v[88:91]
	v_mfma_f32_16x16x32_bf16 v[76:79], v[150:153], v[208:211], v[76:79]
	v_mfma_f32_16x16x32_bf16 v[72:75], v[158:161], v[208:211], v[72:75]
	v_mfma_f32_16x16x32_bf16 v[124:127], v[154:157], v[186:189], v[124:127]
	v_mfma_f32_16x16x32_bf16 v[120:123], v[162:165], v[186:189], v[120:123]
	v_mfma_f32_16x16x32_bf16 v[108:111], v[154:157], v[196:199], v[108:111]
	v_mfma_f32_16x16x32_bf16 v[104:107], v[162:165], v[196:199], v[104:107]
	v_mfma_f32_16x16x32_bf16 v[92:95], v[154:157], v[204:207], v[92:95]
	v_mfma_f32_16x16x32_bf16 v[88:91], v[162:165], v[204:207], v[88:91]
	v_mfma_f32_16x16x32_bf16 v[76:79], v[154:157], v[212:215], v[76:79]
	v_mfma_f32_16x16x32_bf16 v[72:75], v[162:165], v[212:215], v[72:75]
	s_setprio 0
	s_setprio 1
	v_mfma_f32_16x16x32_bf16 v[116:119], v[166:169], v[182:185], v[116:119]
	v_mfma_f32_16x16x32_bf16 v[112:115], v[174:177], v[182:185], v[112:115]
	v_mfma_f32_16x16x32_bf16 v[100:103], v[166:169], v[192:195], v[100:103]
	v_mfma_f32_16x16x32_bf16 v[96:99], v[174:177], v[192:195], v[96:99]
	v_mfma_f32_16x16x32_bf16 v[84:87], v[166:169], v[200:203], v[84:87]
	v_mfma_f32_16x16x32_bf16 v[80:83], v[174:177], v[200:203], v[80:83]
	v_mfma_f32_16x16x32_bf16 v[68:71], v[166:169], v[208:211], v[68:71]
	v_mfma_f32_16x16x32_bf16 v[64:67], v[174:177], v[208:211], v[64:67]
	v_mfma_f32_16x16x32_bf16 v[116:119], v[170:173], v[186:189], v[116:119]
	v_mfma_f32_16x16x32_bf16 v[112:115], v[178:181], v[186:189], v[112:115]
	v_mfma_f32_16x16x32_bf16 v[100:103], v[170:173], v[196:199], v[100:103]
	v_mfma_f32_16x16x32_bf16 v[96:99], v[178:181], v[196:199], v[96:99]
	v_mfma_f32_16x16x32_bf16 v[84:87], v[170:173], v[204:207], v[84:87]
	v_mfma_f32_16x16x32_bf16 v[80:83], v[178:181], v[204:207], v[80:83]
	v_mfma_f32_16x16x32_bf16 v[68:71], v[170:173], v[212:215], v[68:71]
	v_mfma_f32_16x16x32_bf16 v[64:67], v[178:181], v[212:215], v[64:67]
	s_setprio 0
	s_barrier
	s_add_i32 s56, s44, s36
	v_lshl_add_u64 v[216:217], s[30:31], 0, v[132:133]
	s_mov_b32 m0, s56
	ds_read_b128 v[182:185], v149 offset:16384
	ds_read_b128 v[186:189], v149 offset:17408
	ds_read_b128 v[192:195], v149 offset:18432
	ds_read_b128 v[196:199], v149 offset:19456
	ds_read_b128 v[200:203], v149 offset:20480
	ds_read_b128 v[204:207], v149 offset:21504
	ds_read_b128 v[208:211], v149 offset:22528
	ds_read_b128 v[212:215], v149 offset:23552
	global_load_lds_dwordx4 v[216:217], off
	s_add_i32 m0, s56, 0x2000
	s_add_u32 s56, s30, 0x80000
	v_lshl_add_u64 v[218:219], s[30:31], 0, v[128:129]
	s_addc_u32 s57, s31, 0
	s_add_i32 s58, s91, s36
	global_load_lds_dwordx4 v[218:219], off
	s_mov_b32 m0, s58
	v_lshl_add_u64 v[222:223], s[34:35], 0, v[130:131]
	global_load_lds_dwordx4 v132, s[56:57]
	s_add_i32 m0, s58, 0x2000
	s_nop 0
	global_load_lds_dwordx4 v128, s[56:57]
	v_lshl_add_u64 v[220:221], s[34:35], 0, v[134:135]
	s_mov_b32 m0, s27
	s_nop 0
	global_load_lds_dwordx4 v[220:221], off
	s_mov_b32 m0, s38
	s_nop 0
	global_load_lds_dwordx4 v[222:223], off
	s_waitcnt vmcnt(8)
	s_waitcnt lgkmcnt(0)
	s_barrier
; #define PG8_STAGE(bufoff, gbase, voff) do { _Pragma("unroll") for (int _i = 0; _i < 2; ++_i) \
;         __builtin_amdgcn_global_load_lds((const unsigned*)((const char*)(gbase) + (voff)[_i]), (LAS unsigned*)(lds + (bufoff) + ldsw + _i * 8192), 16, 0, 0); } while (0)
; #define PG8_LDA(dst, b, h) do { _Pragma("unroll") for (int m = 0; m < 4; ++m) _Pragma("unroll") for (int k = 0; k < 2; ++k) dst[m][k] = *(const LAS bf16x8*)(lds + PG8_SA(b, h) + aoff + m * 2048 + k * 1024); } while (0)
; #define PG8_LDB(dst, b, h) do { _Pragma("unroll") for (int n = 0; n < 2; ++n) _Pragma("unroll") for (int k = 0; k < 2; ++k) dst[n][k] = *(const LAS bf16x8*)(lds + PG8_SB(b, h) + boff + n * 2048 + k * 1024); } while (0)
; #define PG8_WAIT_V(n) asm volatile("s_waitcnt vmcnt(" #n ")" ::: "memory")
; #define PG8_WAIT_L(n) asm volatile("s_waitcnt lgkmcnt(" #n ")" ::: "memory")
; #define PG8_BAR __builtin_amdgcn_s_barrier()
; #define PG8_SCHED __builtin_amdgcn_sched_barrier(0)
; template <class Epi, class Sched, bool F8 = false>
; __device__ __forceinline__ void gemm_phase(LAS unsigned char* lds, const Gemm g, const Sched& S, const Epi& E) {
;     ...
;             PG8_WAIT_V(8); PG8_WAIT_L(0); PG8_BAR; PG8_MMA(1, 0, At, B0); PG8_MMA(1, 1, At, B1); PG8_BAR; PG8_SCHED;
;             PG8_LDB(B0, 1, 0); PG8_LDB(B1, 1, 1); PG8_SCHED; PG8_LDA(At, 1, 0); PG8_STAGE(PG8_SA(0, 1), a2 + hstepA, voffA);
;             PG8_WAIT_V(8); PG8_WAIT_L(0); PG8_BAR; PG8_MMA(0, 0, At, B0); PG8_MMA(0, 1, At, B1); PG8_BAR; PG8_SCHED;
	s_setprio 1
	s_waitcnt lgkmcnt(0)
	v_mfma_f32_16x16x32_bf16 v[60:63], v[150:153], v[182:185], v[60:63]
	v_mfma_f32_16x16x32_bf16 v[56:59], v[158:161], v[182:185], v[56:59]
	v_mfma_f32_16x16x32_bf16 v[44:47], v[150:153], v[192:195], v[44:47]
	v_mfma_f32_16x16x32_bf16 v[40:43], v[158:161], v[192:195], v[40:43]
	v_mfma_f32_16x16x32_bf16 v[28:31], v[150:153], v[200:203], v[28:31]
	v_mfma_f32_16x16x32_bf16 v[24:27], v[158:161], v[200:203], v[24:27]
	v_mfma_f32_16x16x32_bf16 v[12:15], v[150:153], v[208:211], v[12:15]
	v_mfma_f32_16x16x32_bf16 v[8:11], v[158:161], v[208:211], v[8:11]
	v_mfma_f32_16x16x32_bf16 v[60:63], v[154:157], v[186:189], v[60:63]
	v_mfma_f32_16x16x32_bf16 v[56:59], v[162:165], v[186:189], v[56:59]
	v_mfma_f32_16x16x32_bf16 v[44:47], v[154:157], v[196:199], v[44:47]
	v_mfma_f32_16x16x32_bf16 v[40:43], v[162:165], v[196:199], v[40:43]
	v_mfma_f32_16x16x32_bf16 v[28:31], v[154:157], v[204:207], v[28:31]
	v_mfma_f32_16x16x32_bf16 v[24:27], v[162:165], v[204:207], v[24:27]
	v_mfma_f32_16x16x32_bf16 v[12:15], v[154:157], v[212:215], v[12:15]
	v_mfma_f32_16x16x32_bf16 v[8:11], v[162:165], v[212:215], v[8:11]
	s_setprio 0
	s_setprio 1
	v_mfma_f32_16x16x32_bf16 v[52:55], v[166:169], v[182:185], v[52:55]
	v_mfma_f32_16x16x32_bf16 v[48:51], v[174:177], v[182:185], v[48:51]
	v_mfma_f32_16x16x32_bf16 v[36:39], v[166:169], v[192:195], v[36:39]
	v_mfma_f32_16x16x32_bf16 v[32:35], v[174:177], v[192:195], v[32:35]
	v_mfma_f32_16x16x32_bf16 v[20:23], v[166:169], v[200:203], v[20:23]
	v_mfma_f32_16x16x32_bf16 v[16:19], v[174:177], v[200:203], v[16:19]
	v_mfma_f32_16x16x32_bf16 v[4:7], v[166:169], v[208:211], v[4:7]
	v_mfma_f32_16x16x32_bf16 v[0:3], v[174:177], v[208:211], v[0:3]
	v_mfma_f32_16x16x32_bf16 v[52:55], v[170:173], v[186:189], v[52:55]
	v_mfma_f32_16x16x32_bf16 v[48:51], v[178:181], v[186:189], v[48:51]
	v_mfma_f32_16x16x32_bf16 v[36:39], v[170:173], v[196:199], v[36:39]
	v_mfma_f32_16x16x32_bf16 v[32:35], v[178:181], v[196:199], v[32:35]
	v_mfma_f32_16x16x32_bf16 v[20:23], v[170:173], v[204:207], v[20:23]
	v_mfma_f32_16x16x32_bf16 v[16:19], v[178:181], v[204:207], v[16:19]
	v_mfma_f32_16x16x32_bf16 v[4:7], v[170:173], v[212:215], v[4:7]
	v_mfma_f32_16x16x32_bf16 v[0:3], v[178:181], v[212:215], v[0:3]
	s_setprio 0
	s_barrier
	s_add_i32 s56, 0, 0x18000
	s_add_i32 s57, 0, 0x1c000
	v_add_u32_e32 v162, s56, v145
	v_add_u32_e32 v178, s57, v145
	ds_read_b128 v[150:153], v162
	ds_read_b128 v[154:157], v162 offset:1024
	ds_read_b128 v[158:161], v162 offset:2048
	ds_read_b128 v[162:165], v162 offset:3072
	ds_read_b128 v[166:169], v178
	ds_read_b128 v[170:173], v178 offset:1024
	ds_read_b128 v[174:177], v178 offset:2048
	ds_read_b128 v[178:181], v178 offset:3072
	s_add_u32 s34, s34, 0x80000
	s_addc_u32 s35, s35, 0
	s_mov_b32 m0, s39
	ds_read_b128 v[182:185], v149 offset:32768
	ds_read_b128 v[186:189], v149 offset:33792
	ds_read_b128 v[192:195], v149 offset:34816
	ds_read_b128 v[196:199], v149 offset:35840
	ds_read_b128 v[200:203], v149 offset:36864
	ds_read_b128 v[204:207], v149 offset:37888
	ds_read_b128 v[208:211], v149 offset:38912
	ds_read_b128 v[212:215], v149 offset:39936
	global_load_lds_dwordx4 v134, s[34:35]
	s_mov_b32 m0, s40
	s_nop 0
	global_load_lds_dwordx4 v130, s[34:35]
	s_waitcnt vmcnt(8)
	s_waitcnt lgkmcnt(0)
	s_barrier
	s_setprio 1
	s_waitcnt lgkmcnt(0)
	v_mfma_f32_16x16x32_bf16 v[124:127], v[150:153], v[182:185], v[124:127]
	v_mfma_f32_16x16x32_bf16 v[120:123], v[158:161], v[182:185], v[120:123]
	v_mfma_f32_16x16x32_bf16 v[108:111], v[150:153], v[192:195], v[108:111]
	v_mfma_f32_16x16x32_bf16 v[104:107], v[158:161], v[192:195], v[104:107]
	v_mfma_f32_16x16x32_bf16 v[92:95], v[150:153], v[200:203], v[92:95]
	v_mfma_f32_16x16x32_bf16 v[88:91], v[158:161], v[200:203], v[88:91]
	v_mfma_f32_16x16x32_bf16 v[76:79], v[150:153], v[208:211], v[76:79]
	v_mfma_f32_16x16x32_bf16 v[72:75], v[158:161], v[208:211], v[72:75]
	v_mfma_f32_16x16x32_bf16 v[124:127], v[154:157], v[186:189], v[124:127]
	v_mfma_f32_16x16x32_bf16 v[120:123], v[162:165], v[186:189], v[120:123]
	v_mfma_f32_16x16x32_bf16 v[108:111], v[154:157], v[196:199], v[108:111]
	v_mfma_f32_16x16x32_bf16 v[104:107], v[162:165], v[196:199], v[104:107]
	v_mfma_f32_16x16x32_bf16 v[92:95], v[154:157], v[204:207], v[92:95]
	v_mfma_f32_16x16x32_bf16 v[88:91], v[162:165], v[204:207], v[88:91]
	v_mfma_f32_16x16x32_bf16 v[76:79], v[154:157], v[212:215], v[76:79]
	v_mfma_f32_16x16x32_bf16 v[72:75], v[162:165], v[212:215], v[72:75]
	s_setprio 0
	s_setprio 1
	v_mfma_f32_16x16x32_bf16 v[116:119], v[166:169], v[182:185], v[116:119]
	v_mfma_f32_16x16x32_bf16 v[112:115], v[174:177], v[182:185], v[112:115]
	v_mfma_f32_16x16x32_bf16 v[100:103], v[166:169], v[192:195], v[100:103]
	v_mfma_f32_16x16x32_bf16 v[96:99], v[174:177], v[192:195], v[96:99]
	v_mfma_f32_16x16x32_bf16 v[84:87], v[166:169], v[200:203], v[84:87]
	v_mfma_f32_16x16x32_bf16 v[80:83], v[174:177], v[200:203], v[80:83]
	v_mfma_f32_16x16x32_bf16 v[68:71], v[166:169], v[208:211], v[68:71]
	v_mfma_f32_16x16x32_bf16 v[64:67], v[174:177], v[208:211], v[64:67]
	v_mfma_f32_16x16x32_bf16 v[116:119], v[170:173], v[186:189], v[116:119]
	v_mfma_f32_16x16x32_bf16 v[112:115], v[178:181], v[186:189], v[112:115]
	v_mfma_f32_16x16x32_bf16 v[100:103], v[170:173], v[196:199], v[100:103]
	v_mfma_f32_16x16x32_bf16 v[96:99], v[178:181], v[196:199], v[96:99]
	v_mfma_f32_16x16x32_bf16 v[84:87], v[170:173], v[204:207], v[84:87]
	v_mfma_f32_16x16x32_bf16 v[80:83], v[178:181], v[204:207], v[80:83]
	v_mfma_f32_16x16x32_bf16 v[68:71], v[170:173], v[212:215], v[68:71]
	v_mfma_f32_16x16x32_bf16 v[64:67], v[178:181], v[212:215], v[64:67]
	s_setprio 0
	s_barrier
; #define PG8_STAGE(bufoff, gbase, voff) do { _Pragma("unroll") for (int _i = 0; _i < 2; ++_i) \
;         __builtin_amdgcn_global_load_lds((const unsigned*)((const char*)(gbase) + (voff)[_i]), (LAS unsigned*)(lds + (bufoff) + ldsw + _i * 8192), 16, 0, 0); } while (0)
; #define PG8_LDA(dst, b, h) do { _Pragma("unroll") for (int m = 0; m < 4; ++m) _Pragma("unroll") for (int k = 0; k < 2; ++k) dst[m][k] = *(const LAS bf16x8*)(lds + PG8_SA(b, h) + aoff + m * 2048 + k * 1024); } while (0)
; #define PG8_WAIT_V(n) asm volatile("s_waitcnt vmcnt(" #n ")" ::: "memory")
; #define PG8_WAIT_L(n) asm volatile("s_waitcnt lgkmcnt(" #n ")" ::: "memory")
; #define PG8_BAR __builtin_amdgcn_s_barrier()
; #define PG8_SCHED __builtin_amdgcn_sched_barrier(0)
; template <class Epi, class Sched, bool F8 = false>
; __device__ __forceinline__ void gemm_phase(LAS unsigned char* lds, const Gemm g, const Sched& S, const Epi& E) {
;     ...
;             PG8_LDA(At, 1, 1); PG8_STAGE(PG8_SB(1, 0), b3, voffB); PG8_STAGE(PG8_SB(1, 1), b3 + hstepB, voffB); PG8_STAGE(PG8_SA(1, 0), a3, voffA);
;             PG8_WAIT_V(8); PG8_WAIT_L(0); PG8_BAR; PG8_MMA(1, 0, At, B0); PG8_MMA(1, 1, At, B1); PG8_BAR; PG8_SCHED;
;         }
;         if (wr == 0) PG8_BAR;
	s_add_i32 s34, s56, s36
	s_add_i32 m0, s34, 0xffffff80
	ds_read_b128 v[182:185], v149 offset:49152
	ds_read_b128 v[186:189], v149 offset:50176
	ds_read_b128 v[192:195], v149 offset:51200
	ds_read_b128 v[196:199], v149 offset:52224
	ds_read_b128 v[200:203], v149 offset:53248
	ds_read_b128 v[204:207], v149 offset:54272
	ds_read_b128 v[208:211], v149 offset:55296
	ds_read_b128 v[212:215], v149 offset:56320
	global_load_lds_dwordx4 v[216:217], off offset:128
	s_add_i32 m0, s34, 0x1f80
	s_add_u32 s30, s30, 0x80080
	s_addc_u32 s31, s31, 0
	s_add_i32 s34, s57, s36
	global_load_lds_dwordx4 v[218:219], off offset:128
	s_mov_b32 m0, s34
	s_nop 0
	global_load_lds_dwordx4 v132, s[30:31]
	s_add_i32 m0, s34, 0x2000
	s_nop 0
	global_load_lds_dwordx4 v128, s[30:31]
	s_add_i32 m0, s42, 0xffffff80
	s_nop 0
	global_load_lds_dwordx4 v[220:221], off offset:128
	s_add_i32 m0, s43, 0xffffff80
	s_nop 0
	global_load_lds_dwordx4 v[222:223], off offset:128
	s_waitcnt vmcnt(8)
	s_waitcnt lgkmcnt(0)
	s_barrier
	s_setprio 1
	s_waitcnt lgkmcnt(0)
	v_mfma_f32_16x16x32_bf16 v[60:63], v[150:153], v[182:185], v[60:63]
	v_mfma_f32_16x16x32_bf16 v[56:59], v[158:161], v[182:185], v[56:59]
	v_mfma_f32_16x16x32_bf16 v[44:47], v[150:153], v[192:195], v[44:47]
	v_mfma_f32_16x16x32_bf16 v[40:43], v[158:161], v[192:195], v[40:43]
	v_mfma_f32_16x16x32_bf16 v[28:31], v[150:153], v[200:203], v[28:31]
	v_mfma_f32_16x16x32_bf16 v[24:27], v[158:161], v[200:203], v[24:27]
	v_mfma_f32_16x16x32_bf16 v[12:15], v[150:153], v[208:211], v[12:15]
	v_mfma_f32_16x16x32_bf16 v[8:11], v[158:161], v[208:211], v[8:11]
	v_mfma_f32_16x16x32_bf16 v[60:63], v[154:157], v[186:189], v[60:63]
	v_mfma_f32_16x16x32_bf16 v[56:59], v[162:165], v[186:189], v[56:59]
	v_mfma_f32_16x16x32_bf16 v[44:47], v[154:157], v[196:199], v[44:47]
	v_mfma_f32_16x16x32_bf16 v[40:43], v[162:165], v[196:199], v[40:43]
	v_mfma_f32_16x16x32_bf16 v[28:31], v[154:157], v[204:207], v[28:31]
	v_mfma_f32_16x16x32_bf16 v[24:27], v[162:165], v[204:207], v[24:27]
	v_mfma_f32_16x16x32_bf16 v[12:15], v[154:157], v[212:215], v[12:15]
	v_mfma_f32_16x16x32_bf16 v[8:11], v[162:165], v[212:215], v[8:11]
	s_setprio 0
	s_setprio 1
	v_mfma_f32_16x16x32_bf16 v[52:55], v[166:169], v[182:185], v[52:55]
	v_mfma_f32_16x16x32_bf16 v[48:51], v[174:177], v[182:185], v[48:51]
	v_mfma_f32_16x16x32_bf16 v[36:39], v[166:169], v[192:195], v[36:39]
	v_mfma_f32_16x16x32_bf16 v[32:35], v[174:177], v[192:195], v[32:35]
	v_mfma_f32_16x16x32_bf16 v[20:23], v[166:169], v[200:203], v[20:23]
	v_mfma_f32_16x16x32_bf16 v[16:19], v[174:177], v[200:203], v[16:19]
	v_mfma_f32_16x16x32_bf16 v[4:7], v[166:169], v[208:211], v[4:7]
	v_mfma_f32_16x16x32_bf16 v[0:3], v[174:177], v[208:211], v[0:3]
	v_mfma_f32_16x16x32_bf16 v[52:55], v[170:173], v[186:189], v[52:55]
	v_mfma_f32_16x16x32_bf16 v[48:51], v[178:181], v[186:189], v[48:51]
	v_mfma_f32_16x16x32_bf16 v[36:39], v[170:173], v[196:199], v[36:39]
	v_mfma_f32_16x16x32_bf16 v[32:35], v[178:181], v[196:199], v[32:35]
	v_mfma_f32_16x16x32_bf16 v[20:23], v[170:173], v[204:207], v[20:23]
	v_mfma_f32_16x16x32_bf16 v[16:19], v[178:181], v[204:207], v[16:19]
	v_mfma_f32_16x16x32_bf16 v[4:7], v[170:173], v[212:215], v[4:7]
	v_mfma_f32_16x16x32_bf16 v[0:3], v[178:181], v[212:215], v[0:3]
	s_setprio 0
	s_barrier
	s_add_i32 s53, s53, 2
	s_add_u32 s28, s28, 0x100
	s_addc_u32 s29, s29, 0
	s_add_u32 s50, s50, 0x100
	s_addc_u32 s51, s51, 0
	s_cmp_gt_u32 s53, 29
	s_cbranch_scc0 .LBB0_954
	s_and_b64 vcc, exec, s[14:15]
	s_cbranch_vccz .LBB0_957
	s_barrier

; #define PG8_STAGE(bufoff, gbase, voff) do { _Pragma("unroll") for (int _i = 0; _i < 2; ++_i) \
;         __builtin_amdgcn_global_load_lds((const unsigned*)((const char*)(gbase) + (voff)[_i]), (LAS unsigned*)(lds + (bufoff) + ldsw + _i * 8192), 16, 0, 0); } while (0)
; #define PG8_LDA(dst, b, h) do { _Pragma("unroll") for (int m = 0; m < 4; ++m) _Pragma("unroll") for (int k = 0; k < 2; ++k) dst[m][k] = *(const LAS bf16x8*)(lds + PG8_SA(b, h) + aoff + m * 2048 + k * 1024); } while (0)
; #define PG8_LDB(dst, b, h) do { _Pragma("unroll") for (int n = 0; n < 2; ++n) _Pragma("unroll") for (int k = 0; k < 2; ++k) dst[n][k] = *(const LAS bf16x8*)(lds + PG8_SB(b, h) + boff + n * 2048 + k * 1024); } while (0)
; #define PG8_WAIT_V(n) asm volatile("s_waitcnt vmcnt(" #n ")" ::: "memory")
; #define PG8_WAIT_L(n) asm volatile("s_waitcnt lgkmcnt(" #n ")" ::: "memory")
; #define PG8_BAR __builtin_amdgcn_s_barrier()
; #define PG8_SCHED __builtin_amdgcn_sched_barrier(0)
; template <class Epi, class Sched, bool F8 = false>
; __device__ __forceinline__ void gemm_phase(LAS unsigned char* lds, const Gemm g, const Sched& S, const Epi& E) {
;     ...
;         for (int t = 0; t < nt; t += 2) {
;             const bool last = (t == nt - 2);
;             const char* a1 = cA + (size_t)(t + 1) * kstep;
;             const char* a2 = last ? nA : cA + (size_t)(t + 2) * kstep; const char* b2 = last ? nB : cB + (size_t)(t + 2) * kstep;
;             const char* a3 = a2 + kstep; const char* b3 = b2 + kstep;
;             PG8_LDB(B0, 0, 0); PG8_LDB(B1, 0, 1); PG8_SCHED; PG8_LDA(At, 0, 0); PG8_STAGE(PG8_SA(1, 1), a1 + hstepA, voffA);
;             PG8_WAIT_V(8); PG8_WAIT_L(0); PG8_BAR; PG8_MMA(0, 0, At, B0); PG8_MMA(0, 1, At, B1); PG8_BAR; PG8_SCHED;
;             PG8_LDA(At, 0, 1); PG8_STAGE(PG8_SB(0, 0), b2, voffB); PG8_STAGE(PG8_SB(0, 1), b2 + hstepB, voffB); PG8_STAGE(PG8_SA(0, 0), a2, voffA);
.LBB0_1030:
	ds_read_b128 v[144:147], v183
	ds_read_b128 v[148:151], v183 offset:1024
	ds_read_b128 v[152:155], v183 offset:2048
	ds_read_b128 v[156:159], v183 offset:3072
	ds_read_b128 v[160:163], v184
	ds_read_b128 v[164:167], v184 offset:1024
	ds_read_b128 v[168:171], v184 offset:2048
	ds_read_b128 v[172:175], v184 offset:3072
	s_add_u32 s28, s26, 0x100
	s_addc_u32 s29, s27, 0
	s_cmpk_eq_i32 s53, 0x54
	s_cselect_b32 s35, s9, s29
	s_cselect_b32 s34, s8, s28
	s_cselect_b32 s31, s25, s51
	s_cselect_b32 s30, s24, s50
	s_add_i32 m0, s37, 0xc000
	ds_read_b128 v[176:179], v185
	ds_read_b128 v[186:189], v185 offset:1024
	ds_read_b128 v[192:195], v185 offset:2048
	ds_read_b128 v[196:199], v185 offset:3072
	ds_read_b128 v[200:203], v185 offset:4096
	ds_read_b128 v[204:207], v185 offset:5120
	ds_read_b128 v[208:211], v185 offset:6144
	ds_read_b128 v[212:215], v185 offset:7168
	global_load_lds_dwordx4 v136, s[26:27]
	s_add_i32 m0, s37, 0xe000
	s_nop 0
	global_load_lds_dwordx4 v138, s[26:27]
	s_waitcnt vmcnt(8)
	s_waitcnt lgkmcnt(0)
	s_barrier
	s_setprio 1
	s_waitcnt lgkmcnt(0)
	v_mfma_f32_16x16x32_bf16 v[124:127], v[144:147], v[176:179], v[124:127]
	v_mfma_f32_16x16x32_bf16 v[120:123], v[152:155], v[176:179], v[120:123]
	v_mfma_f32_16x16x32_bf16 v[108:111], v[144:147], v[192:195], v[108:111]
	v_mfma_f32_16x16x32_bf16 v[104:107], v[152:155], v[192:195], v[104:107]
	v_mfma_f32_16x16x32_bf16 v[92:95], v[144:147], v[200:203], v[92:95]
	v_mfma_f32_16x16x32_bf16 v[88:91], v[152:155], v[200:203], v[88:91]
	v_mfma_f32_16x16x32_bf16 v[76:79], v[144:147], v[208:211], v[76:79]
	v_mfma_f32_16x16x32_bf16 v[72:75], v[152:155], v[208:211], v[72:75]
	v_mfma_f32_16x16x32_bf16 v[124:127], v[148:151], v[186:189], v[124:127]
	v_mfma_f32_16x16x32_bf16 v[120:123], v[156:159], v[186:189], v[120:123]
	v_mfma_f32_16x16x32_bf16 v[108:111], v[148:151], v[196:199], v[108:111]
	v_mfma_f32_16x16x32_bf16 v[104:107], v[156:159], v[196:199], v[104:107]
	v_mfma_f32_16x16x32_bf16 v[92:95], v[148:151], v[204:207], v[92:95]
	v_mfma_f32_16x16x32_bf16 v[88:91], v[156:159], v[204:207], v[88:91]
	v_mfma_f32_16x16x32_bf16 v[76:79], v[148:151], v[212:215], v[76:79]
	v_mfma_f32_16x16x32_bf16 v[72:75], v[156:159], v[212:215], v[72:75]
	s_setprio 0
	s_setprio 1
	v_mfma_f32_16x16x32_bf16 v[116:119], v[160:163], v[176:179], v[116:119]
	v_mfma_f32_16x16x32_bf16 v[112:115], v[168:171], v[176:179], v[112:115]
	v_mfma_f32_16x16x32_bf16 v[100:103], v[160:163], v[192:195], v[100:103]
	v_mfma_f32_16x16x32_bf16 v[96:99], v[168:171], v[192:195], v[96:99]
	v_mfma_f32_16x16x32_bf16 v[84:87], v[160:163], v[200:203], v[84:87]
	v_mfma_f32_16x16x32_bf16 v[80:83], v[168:171], v[200:203], v[80:83]
	v_mfma_f32_16x16x32_bf16 v[68:71], v[160:163], v[208:211], v[68:71]
	v_mfma_f32_16x16x32_bf16 v[64:67], v[168:171], v[208:211], v[64:67]
	v_mfma_f32_16x16x32_bf16 v[116:119], v[164:167], v[186:189], v[116:119]
	v_mfma_f32_16x16x32_bf16 v[112:115], v[172:175], v[186:189], v[112:115]
	v_mfma_f32_16x16x32_bf16 v[100:103], v[164:167], v[196:199], v[100:103]
	v_mfma_f32_16x16x32_bf16 v[96:99], v[172:175], v[196:199], v[96:99]
	v_mfma_f32_16x16x32_bf16 v[84:87], v[164:167], v[204:207], v[84:87]
	v_mfma_f32_16x16x32_bf16 v[80:83], v[172:175], v[204:207], v[80:83]
	v_mfma_f32_16x16x32_bf16 v[68:71], v[164:167], v[212:215], v[68:71]
	v_mfma_f32_16x16x32_bf16 v[64:67], v[172:175], v[212:215], v[64:67]
	s_setprio 0
	s_barrier
	s_add_i32 s26, s44, s23
	v_lshl_add_u64 v[216:217], s[30:31], 0, v[132:133]
	s_mov_b32 m0, s26
	ds_read_b128 v[176:179], v185 offset:16384
	ds_read_b128 v[186:189], v185 offset:17408
	ds_read_b128 v[192:195], v185 offset:18432
	ds_read_b128 v[196:199], v185 offset:19456
	ds_read_b128 v[200:203], v185 offset:20480
	ds_read_b128 v[204:207], v185 offset:21504
	ds_read_b128 v[208:211], v185 offset:22528
	ds_read_b128 v[212:215], v185 offset:23552
	global_load_lds_dwordx4 v[216:217], off
	s_add_i32 m0, s26, 0x2000
	s_add_u32 s26, s30, 0x160000
	v_lshl_add_u64 v[218:219], s[30:31], 0, v[128:129]
	s_addc_u32 s27, s31, 0
	s_add_i32 s56, s91, s23
	global_load_lds_dwordx4 v[218:219], off
	s_mov_b32 m0, s56
	v_lshl_add_u64 v[222:223], s[34:35], 0, v[130:131]
	global_load_lds_dwordx4 v132, s[26:27]
	s_add_i32 m0, s56, 0x2000
	s_nop 0
	global_load_lds_dwordx4 v128, s[26:27]
	v_lshl_add_u64 v[220:221], s[34:35], 0, v[134:135]
	s_mov_b32 m0, s37
	s_nop 0
	global_load_lds_dwordx4 v[220:221], off
	s_mov_b32 m0, s38
	s_nop 0
	global_load_lds_dwordx4 v[222:223], off
	s_waitcnt vmcnt(8)
	s_waitcnt lgkmcnt(0)
	s_barrier
; #define PG8_STAGE(bufoff, gbase, voff) do { _Pragma("unroll") for (int _i = 0; _i < 2; ++_i) \
;         __builtin_amdgcn_global_load_lds((const unsigned*)((const char*)(gbase) + (voff)[_i]), (LAS unsigned*)(lds + (bufoff) + ldsw + _i * 8192), 16, 0, 0); } while (0)
; #define PG8_LDA(dst, b, h) do { _Pragma("unroll") for (int m = 0; m < 4; ++m) _Pragma("unroll") for (int k = 0; k < 2; ++k) dst[m][k] = *(const LAS bf16x8*)(lds + PG8_SA(b, h) + aoff + m * 2048 + k * 1024); } while (0)
; #define PG8_LDB(dst, b, h) do { _Pragma("unroll") for (int n = 0; n < 2; ++n) _Pragma("unroll") for (int k = 0; k < 2; ++k) dst[n][k] = *(const LAS bf16x8*)(lds + PG8_SB(b, h) + boff + n * 2048 + k * 1024); } while (0)
; #define PG8_WAIT_V(n) asm volatile("s_waitcnt vmcnt(" #n ")" ::: "memory")
; #define PG8_WAIT_L(n) asm volatile("s_waitcnt lgkmcnt(" #n ")" ::: "memory")
; #define PG8_BAR __builtin_amdgcn_s_barrier()
; #define PG8_SCHED __builtin_amdgcn_sched_barrier(0)
; template <class Epi, class Sched, bool F8 = false>
; __device__ __forceinline__ void gemm_phase(LAS unsigned char* lds, const Gemm g, const Sched& S, const Epi& E) {
;     ...
;             PG8_WAIT_V(8); PG8_WAIT_L(0); PG8_BAR; PG8_MMA(1, 0, At, B0); PG8_MMA(1, 1, At, B1); PG8_BAR; PG8_SCHED;
;             PG8_LDB(B0, 1, 0); PG8_LDB(B1, 1, 1); PG8_SCHED; PG8_LDA(At, 1, 0); PG8_STAGE(PG8_SA(0, 1), a2 + hstepA, voffA);
;             PG8_WAIT_V(8); PG8_WAIT_L(0); PG8_BAR; PG8_MMA(0, 0, At, B0); PG8_MMA(0, 1, At, B1); PG8_BAR; PG8_SCHED;
	s_setprio 1
	s_waitcnt lgkmcnt(0)
	v_mfma_f32_16x16x32_bf16 v[60:63], v[144:147], v[176:179], v[60:63]
	v_mfma_f32_16x16x32_bf16 v[56:59], v[152:155], v[176:179], v[56:59]
	v_mfma_f32_16x16x32_bf16 v[44:47], v[144:147], v[192:195], v[44:47]
	v_mfma_f32_16x16x32_bf16 v[40:43], v[152:155], v[192:195], v[40:43]
	v_mfma_f32_16x16x32_bf16 v[28:31], v[144:147], v[200:203], v[28:31]
	v_mfma_f32_16x16x32_bf16 v[24:27], v[152:155], v[200:203], v[24:27]
	v_mfma_f32_16x16x32_bf16 v[12:15], v[144:147], v[208:211], v[12:15]
	v_mfma_f32_16x16x32_bf16 v[8:11], v[152:155], v[208:211], v[8:11]
	v_mfma_f32_16x16x32_bf16 v[60:63], v[148:151], v[186:189], v[60:63]
	v_mfma_f32_16x16x32_bf16 v[56:59], v[156:159], v[186:189], v[56:59]
	v_mfma_f32_16x16x32_bf16 v[44:47], v[148:151], v[196:199], v[44:47]
	v_mfma_f32_16x16x32_bf16 v[40:43], v[156:159], v[196:199], v[40:43]
	v_mfma_f32_16x16x32_bf16 v[28:31], v[148:151], v[204:207], v[28:31]
	v_mfma_f32_16x16x32_bf16 v[24:27], v[156:159], v[204:207], v[24:27]
	v_mfma_f32_16x16x32_bf16 v[12:15], v[148:151], v[212:215], v[12:15]
	v_mfma_f32_16x16x32_bf16 v[8:11], v[156:159], v[212:215], v[8:11]
	s_setprio 0
	s_setprio 1
	v_mfma_f32_16x16x32_bf16 v[52:55], v[160:163], v[176:179], v[52:55]
	v_mfma_f32_16x16x32_bf16 v[48:51], v[168:171], v[176:179], v[48:51]
	v_mfma_f32_16x16x32_bf16 v[36:39], v[160:163], v[192:195], v[36:39]
	v_mfma_f32_16x16x32_bf16 v[32:35], v[168:171], v[192:195], v[32:35]
	v_mfma_f32_16x16x32_bf16 v[20:23], v[160:163], v[200:203], v[20:23]
	v_mfma_f32_16x16x32_bf16 v[16:19], v[168:171], v[200:203], v[16:19]
	v_mfma_f32_16x16x32_bf16 v[4:7], v[160:163], v[208:211], v[4:7]
	v_mfma_f32_16x16x32_bf16 v[0:3], v[168:171], v[208:211], v[0:3]
	v_mfma_f32_16x16x32_bf16 v[52:55], v[164:167], v[186:189], v[52:55]
	v_mfma_f32_16x16x32_bf16 v[48:51], v[172:175], v[186:189], v[48:51]
	v_mfma_f32_16x16x32_bf16 v[36:39], v[164:167], v[196:199], v[36:39]
	v_mfma_f32_16x16x32_bf16 v[32:35], v[172:175], v[196:199], v[32:35]
	v_mfma_f32_16x16x32_bf16 v[20:23], v[164:167], v[204:207], v[20:23]
	v_mfma_f32_16x16x32_bf16 v[16:19], v[172:175], v[204:207], v[16:19]
	v_mfma_f32_16x16x32_bf16 v[4:7], v[164:167], v[212:215], v[4:7]
	v_mfma_f32_16x16x32_bf16 v[0:3], v[172:175], v[212:215], v[0:3]
	s_setprio 0
	s_barrier
	s_add_i32 s56, 0, 0x18000
	s_add_i32 s57, 0, 0x1c000
	v_add_u32_e32 v156, s56, v181
	v_add_u32_e32 v172, s57, v181
	ds_read_b128 v[144:147], v156
	ds_read_b128 v[148:151], v156 offset:1024
	ds_read_b128 v[152:155], v156 offset:2048
	ds_read_b128 v[156:159], v156 offset:3072
	ds_read_b128 v[160:163], v172
	ds_read_b128 v[164:167], v172 offset:1024
	ds_read_b128 v[168:171], v172 offset:2048
	ds_read_b128 v[172:175], v172 offset:3072
	s_add_u32 s26, s34, 0x160000
	s_addc_u32 s27, s35, 0
	s_mov_b32 m0, s39
	ds_read_b128 v[176:179], v185 offset:32768
	ds_read_b128 v[186:189], v185 offset:33792
	ds_read_b128 v[192:195], v185 offset:34816
	ds_read_b128 v[196:199], v185 offset:35840
	ds_read_b128 v[200:203], v185 offset:36864
	ds_read_b128 v[204:207], v185 offset:37888
	ds_read_b128 v[208:211], v185 offset:38912
	ds_read_b128 v[212:215], v185 offset:39936
	global_load_lds_dwordx4 v134, s[26:27]
	s_mov_b32 m0, s40
	s_nop 0
	global_load_lds_dwordx4 v130, s[26:27]
	s_waitcnt vmcnt(8)
	s_waitcnt lgkmcnt(0)
	s_barrier
	s_setprio 1
	s_waitcnt lgkmcnt(0)
	v_mfma_f32_16x16x32_bf16 v[124:127], v[144:147], v[176:179], v[124:127]
	v_mfma_f32_16x16x32_bf16 v[120:123], v[152:155], v[176:179], v[120:123]
	v_mfma_f32_16x16x32_bf16 v[108:111], v[144:147], v[192:195], v[108:111]
	v_mfma_f32_16x16x32_bf16 v[104:107], v[152:155], v[192:195], v[104:107]
	v_mfma_f32_16x16x32_bf16 v[92:95], v[144:147], v[200:203], v[92:95]
	v_mfma_f32_16x16x32_bf16 v[88:91], v[152:155], v[200:203], v[88:91]
	v_mfma_f32_16x16x32_bf16 v[76:79], v[144:147], v[208:211], v[76:79]
	v_mfma_f32_16x16x32_bf16 v[72:75], v[152:155], v[208:211], v[72:75]
	v_mfma_f32_16x16x32_bf16 v[124:127], v[148:151], v[186:189], v[124:127]
	v_mfma_f32_16x16x32_bf16 v[120:123], v[156:159], v[186:189], v[120:123]
	v_mfma_f32_16x16x32_bf16 v[108:111], v[148:151], v[196:199], v[108:111]
	v_mfma_f32_16x16x32_bf16 v[104:107], v[156:159], v[196:199], v[104:107]
	v_mfma_f32_16x16x32_bf16 v[92:95], v[148:151], v[204:207], v[92:95]
	v_mfma_f32_16x16x32_bf16 v[88:91], v[156:159], v[204:207], v[88:91]
	v_mfma_f32_16x16x32_bf16 v[76:79], v[148:151], v[212:215], v[76:79]
	v_mfma_f32_16x16x32_bf16 v[72:75], v[156:159], v[212:215], v[72:75]
	s_setprio 0
	s_setprio 1
	v_mfma_f32_16x16x32_bf16 v[116:119], v[160:163], v[176:179], v[116:119]
	v_mfma_f32_16x16x32_bf16 v[112:115], v[168:171], v[176:179], v[112:115]
	v_mfma_f32_16x16x32_bf16 v[100:103], v[160:163], v[192:195], v[100:103]
	v_mfma_f32_16x16x32_bf16 v[96:99], v[168:171], v[192:195], v[96:99]
	v_mfma_f32_16x16x32_bf16 v[84:87], v[160:163], v[200:203], v[84:87]
	v_mfma_f32_16x16x32_bf16 v[80:83], v[168:171], v[200:203], v[80:83]
	v_mfma_f32_16x16x32_bf16 v[68:71], v[160:163], v[208:211], v[68:71]
	v_mfma_f32_16x16x32_bf16 v[64:67], v[168:171], v[208:211], v[64:67]
	v_mfma_f32_16x16x32_bf16 v[116:119], v[164:167], v[186:189], v[116:119]
	v_mfma_f32_16x16x32_bf16 v[112:115], v[172:175], v[186:189], v[112:115]
	v_mfma_f32_16x16x32_bf16 v[100:103], v[164:167], v[196:199], v[100:103]
	v_mfma_f32_16x16x32_bf16 v[96:99], v[172:175], v[196:199], v[96:99]
	v_mfma_f32_16x16x32_bf16 v[84:87], v[164:167], v[204:207], v[84:87]
	v_mfma_f32_16x16x32_bf16 v[80:83], v[172:175], v[204:207], v[80:83]
	v_mfma_f32_16x16x32_bf16 v[68:71], v[164:167], v[212:215], v[68:71]
	v_mfma_f32_16x16x32_bf16 v[64:67], v[172:175], v[212:215], v[64:67]
	s_setprio 0
	s_barrier
; #define PG8_STAGE(bufoff, gbase, voff) do { _Pragma("unroll") for (int _i = 0; _i < 2; ++_i) \
;         __builtin_amdgcn_global_load_lds((const unsigned*)((const char*)(gbase) + (voff)[_i]), (LAS unsigned*)(lds + (bufoff) + ldsw + _i * 8192), 16, 0, 0); } while (0)
; #define PG8_LDA(dst, b, h) do { _Pragma("unroll") for (int m = 0; m < 4; ++m) _Pragma("unroll") for (int k = 0; k < 2; ++k) dst[m][k] = *(const LAS bf16x8*)(lds + PG8_SA(b, h) + aoff + m * 2048 + k * 1024); } while (0)
; #define PG8_WAIT_V(n) asm volatile("s_waitcnt vmcnt(" #n ")" ::: "memory")
; #define PG8_WAIT_L(n) asm volatile("s_waitcnt lgkmcnt(" #n ")" ::: "memory")
; #define PG8_BAR __builtin_amdgcn_s_barrier()
; #define PG8_SCHED __builtin_amdgcn_sched_barrier(0)
; template <class Epi, class Sched, bool F8 = false>
; __device__ __forceinline__ void gemm_phase(LAS unsigned char* lds, const Gemm g, const Sched& S, const Epi& E) {
;     ...
;             PG8_LDA(At, 1, 1); PG8_STAGE(PG8_SB(1, 0), b3, voffB); PG8_STAGE(PG8_SB(1, 1), b3 + hstepB, voffB); PG8_STAGE(PG8_SA(1, 0), a3, voffA);
;             PG8_WAIT_V(8); PG8_WAIT_L(0); PG8_BAR; PG8_MMA(1, 0, At, B0); PG8_MMA(1, 1, At, B1); PG8_BAR; PG8_SCHED;
;         }
;         if (wr == 0) PG8_BAR;
	s_add_i32 s26, s56, s23
	s_add_i32 m0, s26, 0xffffff80
	ds_read_b128 v[176:179], v185 offset:49152
	ds_read_b128 v[186:189], v185 offset:50176
	ds_read_b128 v[192:195], v185 offset:51200
	ds_read_b128 v[196:199], v185 offset:52224
	ds_read_b128 v[200:203], v185 offset:53248
	ds_read_b128 v[204:207], v185 offset:54272
	ds_read_b128 v[208:211], v185 offset:55296
	ds_read_b128 v[212:215], v185 offset:56320
	global_load_lds_dwordx4 v[216:217], off offset:128
	s_add_i32 m0, s26, 0x1f80
	s_add_u32 s26, s30, 0x160080
	s_addc_u32 s27, s31, 0
	s_add_i32 s30, s57, s23
	global_load_lds_dwordx4 v[218:219], off offset:128
	s_mov_b32 m0, s30
	s_nop 0
	global_load_lds_dwordx4 v132, s[26:27]
	s_add_i32 m0, s30, 0x2000
	s_nop 0
	global_load_lds_dwordx4 v128, s[26:27]
	s_add_i32 m0, s42, 0xffffff80
	s_nop 0
	global_load_lds_dwordx4 v[220:221], off offset:128
	s_add_i32 m0, s43, 0xffffff80
	s_nop 0
	global_load_lds_dwordx4 v[222:223], off offset:128
	s_waitcnt vmcnt(8)
	s_waitcnt lgkmcnt(0)
	s_barrier
	s_setprio 1
	s_waitcnt lgkmcnt(0)
	v_mfma_f32_16x16x32_bf16 v[60:63], v[144:147], v[176:179], v[60:63]
	v_mfma_f32_16x16x32_bf16 v[56:59], v[152:155], v[176:179], v[56:59]
	v_mfma_f32_16x16x32_bf16 v[44:47], v[144:147], v[192:195], v[44:47]
	v_mfma_f32_16x16x32_bf16 v[40:43], v[152:155], v[192:195], v[40:43]
	v_mfma_f32_16x16x32_bf16 v[28:31], v[144:147], v[200:203], v[28:31]
	v_mfma_f32_16x16x32_bf16 v[24:27], v[152:155], v[200:203], v[24:27]
	v_mfma_f32_16x16x32_bf16 v[12:15], v[144:147], v[208:211], v[12:15]
	v_mfma_f32_16x16x32_bf16 v[8:11], v[152:155], v[208:211], v[8:11]
	v_mfma_f32_16x16x32_bf16 v[60:63], v[148:151], v[186:189], v[60:63]
	v_mfma_f32_16x16x32_bf16 v[56:59], v[156:159], v[186:189], v[56:59]
	v_mfma_f32_16x16x32_bf16 v[44:47], v[148:151], v[196:199], v[44:47]
	v_mfma_f32_16x16x32_bf16 v[40:43], v[156:159], v[196:199], v[40:43]
	v_mfma_f32_16x16x32_bf16 v[28:31], v[148:151], v[204:207], v[28:31]
	v_mfma_f32_16x16x32_bf16 v[24:27], v[156:159], v[204:207], v[24:27]
	v_mfma_f32_16x16x32_bf16 v[12:15], v[148:151], v[212:215], v[12:15]
	v_mfma_f32_16x16x32_bf16 v[8:11], v[156:159], v[212:215], v[8:11]
	s_setprio 0
	s_setprio 1
	v_mfma_f32_16x16x32_bf16 v[52:55], v[160:163], v[176:179], v[52:55]
	v_mfma_f32_16x16x32_bf16 v[48:51], v[168:171], v[176:179], v[48:51]
	v_mfma_f32_16x16x32_bf16 v[36:39], v[160:163], v[192:195], v[36:39]
	v_mfma_f32_16x16x32_bf16 v[32:35], v[168:171], v[192:195], v[32:35]
	v_mfma_f32_16x16x32_bf16 v[20:23], v[160:163], v[200:203], v[20:23]
	v_mfma_f32_16x16x32_bf16 v[16:19], v[168:171], v[200:203], v[16:19]
	v_mfma_f32_16x16x32_bf16 v[4:7], v[160:163], v[208:211], v[4:7]
	v_mfma_f32_16x16x32_bf16 v[0:3], v[168:171], v[208:211], v[0:3]
	v_mfma_f32_16x16x32_bf16 v[52:55], v[164:167], v[186:189], v[52:55]
	v_mfma_f32_16x16x32_bf16 v[48:51], v[172:175], v[186:189], v[48:51]
	v_mfma_f32_16x16x32_bf16 v[36:39], v[164:167], v[196:199], v[36:39]
	v_mfma_f32_16x16x32_bf16 v[32:35], v[172:175], v[196:199], v[32:35]
	v_mfma_f32_16x16x32_bf16 v[20:23], v[164:167], v[204:207], v[20:23]
	v_mfma_f32_16x16x32_bf16 v[16:19], v[172:175], v[204:207], v[16:19]
	v_mfma_f32_16x16x32_bf16 v[4:7], v[164:167], v[212:215], v[4:7]
	v_mfma_f32_16x16x32_bf16 v[0:3], v[172:175], v[212:215], v[0:3]
	s_setprio 0
	s_barrier
	s_add_i32 s53, s53, 2
	s_add_u32 s50, s50, 0x100
	s_addc_u32 s51, s51, 0
	s_cmpk_gt_u32 s53, 0x55
	s_mov_b64 s[26:27], s[28:29]
	s_cbranch_scc0 .LBB0_1030
	s_and_b64 vcc, exec, s[20:21]
	s_cbranch_vccz .LBB0_1033
	s_barrier
